# diff-attention V-role loops: back edge rotated in front of the latch waits/barrier, on top of S-loop rotation + tree trim
# speedup vs baseline: 1.0036x; 1.0036x over previous
.LBB0_1353:
	s_add_i32 s0, s0, 64
	s_add_i32 s66, s66, 0x8000
	s_cmp_eq_u32 s63, s66
	s_cbranch_scc1 .Lrotv_exit_0
	s_waitcnt vmcnt(0)
	s_waitcnt lgkmcnt(0)
	s_barrier
.LBB0_1354:
	v_mov_b32_e32 v2, v178
	s_ashr_i32 s1, s0, 31
	v_lshrrev_b32_e32 v5, 1, v2
	v_bfe_u32 v4, v2, 2, 2
	v_and_b32_e32 v5, 8, v5
	v_or3_b32 v4, v4, v5, s60
	v_and_b32_e32 v5, 0xffffffe0, v2
	s_lshl_b64 s[68:69], s[0:1], 9
	v_lshlrev_b32_e32 v2, 3, v2
	v_add_u32_e32 v5, s62, v5
	s_add_u32 s68, s55, s68
	v_and_or_b32 v2, v2, 24, v5
	s_addc_u32 s69, s56, s69
	s_and_b32 s1, s66, 0x8000
	v_lshl_add_u32 v4, v4, 8, v2
	s_add_i32 s67, s15, s1
	v_ashrrev_i32_e32 v5, 31, v4
	s_add_i32 s70, s67, 0x4000
	v_lshl_add_u64 v[6:7], v[4:5], 1, s[68:69]
	s_mov_b32 m0, s67
	v_add_u32_e32 v2, s57, v161
	global_load_lds_dwordx4 v[6:7], off
	v_lshl_add_u64 v[6:7], v[6:7], 0, s[12:13]
	s_mov_b32 m0, s70
	s_xor_b32 s1, s1, 0x8000
	global_load_lds_dwordx4 v[6:7], off
	v_add_u32_e32 v6, 0x1000, v4
	v_ashrrev_i32_e32 v7, 31, v6
	v_lshl_add_u64 v[6:7], v[6:7], 1, s[68:69]
	s_add_i32 m0, s67, 0x1000
	v_add_u32_e32 v16, s1, v185
	global_load_lds_dwordx4 v[6:7], off
	v_lshl_add_u64 v[6:7], v[6:7], 0, s[12:13]
	s_add_i32 m0, s67, 0x5000
	s_nop 0
	global_load_lds_dwordx4 v[6:7], off
	v_add_u32_e32 v6, 0x2000, v4
	v_ashrrev_i32_e32 v7, 31, v6
	v_lshl_add_u64 v[6:7], v[6:7], 1, s[68:69]
	s_add_i32 m0, s67, 0x2000
	v_add_u32_e32 v4, 0x3000, v4
	global_load_lds_dwordx4 v[6:7], off
	v_lshl_add_u64 v[6:7], v[6:7], 0, s[12:13]
	s_add_i32 m0, s67, 0x6000
	v_ashrrev_i32_e32 v5, 31, v4
	global_load_lds_dwordx4 v[6:7], off
	v_lshl_add_u64 v[4:5], v[4:5], 1, s[68:69]
	s_add_i32 m0, s67, 0x3000
	s_nop 0
	global_load_lds_dwordx4 v[4:5], off
	v_lshl_add_u64 v[4:5], v[4:5], 0, s[12:13]
	s_add_i32 m0, s67, 0x7000
	s_nop 0
	global_load_lds_dwordx4 v[4:5], off
	ds_read_b128 v[146:149], v2
	ds_read_b128 v[12:15], v2 offset:1024
	ds_read_b128 v[8:11], v2 offset:2048
	ds_read_b128 v[4:7], v2 offset:3072
	s_waitcnt lgkmcnt(0)
	ds_read_b64_tr_b16 v[150:151], v16 offset:0
	ds_read_b64_tr_b16 v[152:153], v16 offset:0x800
	ds_read_b64_tr_b16 v[154:155], v16 offset:0x1000
	ds_read_b64_tr_b16 v[156:157], v16 offset:0x1800
	ds_read_b64_tr_b16 v[214:215], v16 offset:0x2000
	ds_read_b64_tr_b16 v[216:217], v16 offset:0x2800
	ds_read_b64_tr_b16 v[218:219], v16 offset:0x3000
	ds_read_b64_tr_b16 v[220:221], v16 offset:0x3800
	ds_read_b64_tr_b16 v[222:223], v16 offset:0x200
	ds_read_b64_tr_b16 v[224:225], v16 offset:0xa00
	ds_read_b64_tr_b16 v[226:227], v16 offset:0x1200
	ds_read_b64_tr_b16 v[228:229], v16 offset:0x1a00
	ds_read_b64_tr_b16 v[230:231], v16 offset:0x2200
	ds_read_b64_tr_b16 v[232:233], v16 offset:0x2a00
	ds_read_b64_tr_b16 v[234:235], v16 offset:0x3200
	ds_read_b64_tr_b16 v[236:237], v16 offset:0x3a00
	s_waitcnt lgkmcnt(8)
	s_waitcnt lgkmcnt(0)
	v_mfma_f32_32x32x16_bf16 v[114:129], v[146:149], v[150:153], v[114:129]
	v_mfma_f32_32x32x16_bf16 v[114:129], v[12:15], v[154:157], v[114:129]
	v_mfma_f32_32x32x16_bf16 v[114:129], v[8:11], v[214:217], v[114:129]
	v_mfma_f32_32x32x16_bf16 v[114:129], v[4:7], v[218:221], v[114:129]
	ds_read_b64_tr_b16 v[150:151], v16 offset:0x400
	ds_read_b64_tr_b16 v[152:153], v16 offset:0xc00
	ds_read_b64_tr_b16 v[154:155], v16 offset:0x1400
	ds_read_b64_tr_b16 v[156:157], v16 offset:0x1c00
	ds_read_b64_tr_b16 v[214:215], v16 offset:0x2400
	ds_read_b64_tr_b16 v[216:217], v16 offset:0x2c00
	ds_read_b64_tr_b16 v[218:219], v16 offset:0x3400
	ds_read_b64_tr_b16 v[220:221], v16 offset:0x3c00
	s_waitcnt lgkmcnt(8)
	v_mfma_f32_32x32x16_bf16 v[130:145], v[146:149], v[222:225], v[130:145]
	v_mfma_f32_32x32x16_bf16 v[130:145], v[12:15], v[226:229], v[130:145]
	v_mfma_f32_32x32x16_bf16 v[130:145], v[8:11], v[230:233], v[130:145]
	v_mfma_f32_32x32x16_bf16 v[130:145], v[4:7], v[234:237], v[130:145]
	ds_read_b64_tr_b16 v[222:223], v16 offset:0x600
	ds_read_b64_tr_b16 v[224:225], v16 offset:0xe00
	ds_read_b64_tr_b16 v[226:227], v16 offset:0x1600
	ds_read_b64_tr_b16 v[228:229], v16 offset:0x1e00
	ds_read_b64_tr_b16 v[230:231], v16 offset:0x2600
	ds_read_b64_tr_b16 v[232:233], v16 offset:0x2e00
	ds_read_b64_tr_b16 v[234:235], v16 offset:0x3600
	ds_read_b64_tr_b16 v[236:237], v16 offset:0x3e00
	s_waitcnt lgkmcnt(8)
	v_mfma_f32_32x32x16_bf16 v[82:97], v[146:149], v[150:153], v[82:97]
	v_mfma_f32_32x32x16_bf16 v[82:97], v[12:15], v[154:157], v[82:97]
	v_mfma_f32_32x32x16_bf16 v[82:97], v[8:11], v[214:217], v[82:97]
	v_mfma_f32_32x32x16_bf16 v[82:97], v[4:7], v[218:221], v[82:97]
	s_waitcnt lgkmcnt(0)
	v_mfma_f32_32x32x16_bf16 v[98:113], v[146:149], v[222:225], v[98:113]
	s_waitcnt lgkmcnt(0)
	s_barrier
	v_add_u32_e32 v16, 0x4000, v16
	ds_read_b64_tr_b16 v[150:151], v16 offset:0
	ds_read_b64_tr_b16 v[152:153], v16 offset:0x800
	ds_read_b64_tr_b16 v[154:155], v16 offset:0x1000
	ds_read_b64_tr_b16 v[156:157], v16 offset:0x1800
	ds_read_b64_tr_b16 v[214:215], v16 offset:0x2000
	v_mfma_f32_32x32x16_bf16 v[98:113], v[12:15], v[226:229], v[98:113]
	ds_read_b64_tr_b16 v[216:217], v16 offset:0x2800
	ds_read_b64_tr_b16 v[218:219], v16 offset:0x3000
	ds_read_b64_tr_b16 v[220:221], v16 offset:0x3800
	v_mfma_f32_32x32x16_bf16 v[98:113], v[8:11], v[230:233], v[98:113]
	v_mfma_f32_32x32x16_bf16 v[98:113], v[4:7], v[234:237], v[98:113]
	ds_read_b64_tr_b16 v[222:223], v16 offset:0x200
	ds_read_b64_tr_b16 v[224:225], v16 offset:0xa00
	ds_read_b64_tr_b16 v[226:227], v16 offset:0x1200
	ds_read_b64_tr_b16 v[228:229], v16 offset:0x1a00
	ds_read_b64_tr_b16 v[230:231], v16 offset:0x2200
	ds_read_b64_tr_b16 v[232:233], v16 offset:0x2a00
	ds_read_b64_tr_b16 v[234:235], v16 offset:0x3200
	ds_read_b64_tr_b16 v[236:237], v16 offset:0x3a00
	s_waitcnt lgkmcnt(8)
	v_mfma_f32_32x32x16_bf16 v[50:65], v[146:149], v[150:153], v[50:65]
	v_mfma_f32_32x32x16_bf16 v[50:65], v[12:15], v[154:157], v[50:65]
	v_mfma_f32_32x32x16_bf16 v[50:65], v[8:11], v[214:217], v[50:65]
	v_mfma_f32_32x32x16_bf16 v[50:65], v[4:7], v[218:221], v[50:65]
	ds_read_b64_tr_b16 v[150:151], v16 offset:0x400
	ds_read_b64_tr_b16 v[152:153], v16 offset:0xc00
	ds_read_b64_tr_b16 v[154:155], v16 offset:0x1400
	ds_read_b64_tr_b16 v[156:157], v16 offset:0x1c00
	ds_read_b64_tr_b16 v[214:215], v16 offset:0x2400
	ds_read_b64_tr_b16 v[216:217], v16 offset:0x2c00
	ds_read_b64_tr_b16 v[218:219], v16 offset:0x3400
	ds_read_b64_tr_b16 v[220:221], v16 offset:0x3c00
	s_waitcnt lgkmcnt(8)
	v_mfma_f32_32x32x16_bf16 v[66:81], v[146:149], v[222:225], v[66:81]
	v_mfma_f32_32x32x16_bf16 v[66:81], v[12:15], v[226:229], v[66:81]
	v_mfma_f32_32x32x16_bf16 v[66:81], v[8:11], v[230:233], v[66:81]
	v_mfma_f32_32x32x16_bf16 v[66:81], v[4:7], v[234:237], v[66:81]
	ds_read_b64_tr_b16 v[222:223], v16 offset:0x600
	ds_read_b64_tr_b16 v[224:225], v16 offset:0xe00
	ds_read_b64_tr_b16 v[226:227], v16 offset:0x1600
	ds_read_b64_tr_b16 v[228:229], v16 offset:0x1e00
	ds_read_b64_tr_b16 v[230:231], v16 offset:0x2600
	ds_read_b64_tr_b16 v[232:233], v16 offset:0x2e00
	ds_read_b64_tr_b16 v[234:235], v16 offset:0x3600
	ds_read_b64_tr_b16 v[236:237], v16 offset:0x3e00
	s_waitcnt lgkmcnt(8)
	v_mfma_f32_32x32x16_bf16 v[18:33], v[146:149], v[150:153], v[18:33]
	v_mfma_f32_32x32x16_bf16 v[18:33], v[12:15], v[154:157], v[18:33]
	v_mfma_f32_32x32x16_bf16 v[18:33], v[8:11], v[214:217], v[18:33]
	v_mfma_f32_32x32x16_bf16 v[18:33], v[4:7], v[218:221], v[18:33]
	s_waitcnt lgkmcnt(0)
	v_mfma_f32_32x32x16_bf16 v[34:49], v[146:149], v[222:225], v[34:49]
	s_add_i32 s1, s59, 0
	s_add_i32 s1, s1, 0x20000
	v_mfma_f32_32x32x16_bf16 v[34:49], v[12:15], v[226:229], v[34:49]
	v_mfma_f32_32x32x16_bf16 v[34:49], v[8:11], v[230:233], v[34:49]
	v_mov_b32_e32 v8, s1
	ds_read_b32 v8, v8
	s_waitcnt lgkmcnt(0)
	v_readfirstlane_b32 s1, v8
	v_mfma_f32_32x32x16_bf16 v[34:49], v[4:7], v[234:237], v[34:49]
	s_cmp_eq_u32 s1, 0
	s_cbranch_scc1 .LBB0_1353
	v_add_u32_e32 v4, s18, v163
	ds_read_b128 v[146:149], v4 offset:96
	ds_read_b128 v[12:15], v4 offset:64
	ds_read_b128 v[8:11], v4 offset:32
	ds_read_b128 v[4:7], v4
	s_waitcnt lgkmcnt(0)
	v_pk_mul_f32 v[126:127], v[126:127], v[146:147]
	v_pk_mul_f32 v[122:123], v[122:123], v[12:13]
	v_pk_mul_f32 v[118:119], v[118:119], v[8:9]
	v_pk_mul_f32 v[128:129], v[128:129], v[148:149]
	v_pk_mul_f32 v[124:125], v[124:125], v[14:15]
	v_pk_mul_f32 v[120:121], v[120:121], v[10:11]
	v_pk_mul_f32 v[116:117], v[116:117], v[6:7]
	v_pk_mul_f32 v[114:115], v[114:115], v[4:5]
	v_pk_mul_f32 v[142:143], v[142:143], v[146:147]
	v_pk_mul_f32 v[138:139], v[138:139], v[12:13]
	v_pk_mul_f32 v[134:135], v[134:135], v[8:9]
	v_pk_mul_f32 v[144:145], v[144:145], v[148:149]
	v_pk_mul_f32 v[140:141], v[140:141], v[14:15]
	v_pk_mul_f32 v[136:137], v[136:137], v[10:11]
	v_pk_mul_f32 v[132:133], v[132:133], v[6:7]
	v_pk_mul_f32 v[130:131], v[130:131], v[4:5]
	v_pk_mul_f32 v[94:95], v[94:95], v[146:147]
	v_pk_mul_f32 v[90:91], v[90:91], v[12:13]
	v_pk_mul_f32 v[86:87], v[86:87], v[8:9]
	v_pk_mul_f32 v[96:97], v[96:97], v[148:149]
	v_pk_mul_f32 v[92:93], v[92:93], v[14:15]
	v_pk_mul_f32 v[88:89], v[88:89], v[10:11]
	v_pk_mul_f32 v[84:85], v[84:85], v[6:7]
	v_pk_mul_f32 v[82:83], v[82:83], v[4:5]
	v_pk_mul_f32 v[110:111], v[110:111], v[146:147]
	v_pk_mul_f32 v[106:107], v[106:107], v[12:13]
	v_pk_mul_f32 v[102:103], v[102:103], v[8:9]
	v_pk_mul_f32 v[112:113], v[112:113], v[148:149]
	v_pk_mul_f32 v[108:109], v[108:109], v[14:15]
	v_pk_mul_f32 v[104:105], v[104:105], v[10:11]
	v_pk_mul_f32 v[100:101], v[100:101], v[6:7]
	v_pk_mul_f32 v[98:99], v[98:99], v[4:5]
	v_pk_mul_f32 v[62:63], v[62:63], v[146:147]
	v_pk_mul_f32 v[58:59], v[58:59], v[12:13]
	v_pk_mul_f32 v[54:55], v[54:55], v[8:9]
	v_pk_mul_f32 v[64:65], v[64:65], v[148:149]
	v_pk_mul_f32 v[60:61], v[60:61], v[14:15]
	v_pk_mul_f32 v[56:57], v[56:57], v[10:11]
	v_pk_mul_f32 v[52:53], v[52:53], v[6:7]
	v_pk_mul_f32 v[50:51], v[50:51], v[4:5]
	v_pk_mul_f32 v[78:79], v[78:79], v[146:147]
	v_pk_mul_f32 v[74:75], v[74:75], v[12:13]
	v_pk_mul_f32 v[70:71], v[70:71], v[8:9]
	v_pk_mul_f32 v[80:81], v[80:81], v[148:149]
	v_pk_mul_f32 v[76:77], v[76:77], v[14:15]
	v_pk_mul_f32 v[72:73], v[72:73], v[10:11]
	v_pk_mul_f32 v[68:69], v[68:69], v[6:7]
	v_pk_mul_f32 v[66:67], v[66:67], v[4:5]
	v_pk_mul_f32 v[30:31], v[30:31], v[146:147]
	v_pk_mul_f32 v[26:27], v[26:27], v[12:13]
	v_pk_mul_f32 v[22:23], v[22:23], v[8:9]
	v_pk_mul_f32 v[32:33], v[32:33], v[148:149]
	v_pk_mul_f32 v[28:29], v[28:29], v[14:15]
	v_pk_mul_f32 v[24:25], v[24:25], v[10:11]
	v_pk_mul_f32 v[20:21], v[20:21], v[6:7]
	v_pk_mul_f32 v[18:19], v[18:19], v[4:5]
	v_pk_mul_f32 v[46:47], v[46:47], v[146:147]
	v_pk_mul_f32 v[42:43], v[42:43], v[12:13]
	v_pk_mul_f32 v[38:39], v[38:39], v[8:9]
	v_pk_mul_f32 v[48:49], v[48:49], v[148:149]
	v_pk_mul_f32 v[44:45], v[44:45], v[14:15]
	v_pk_mul_f32 v[40:41], v[40:41], v[10:11]
	v_pk_mul_f32 v[36:37], v[36:37], v[6:7]
	v_pk_mul_f32 v[34:35], v[34:35], v[4:5]
	s_branch .LBB0_1353
.Lrotv_exit_0:
	s_waitcnt vmcnt(0)
	s_waitcnt lgkmcnt(0)
	s_barrier
.LBB0_1356:
	ds_read_b128 v[154:157], v2
	ds_read_b128 v[150:153], v2 offset:1024
	ds_read_b128 v[8:11], v2 offset:2048
	ds_read_b128 v[4:7], v2 offset:3072
	s_waitcnt lgkmcnt(0)
	ds_read_b64_tr_b16 v[12:13], v187 offset:0
	ds_read_b64_tr_b16 v[14:15], v187 offset:0x800
	ds_read_b64_tr_b16 v[146:147], v187 offset:0x1000
	ds_read_b64_tr_b16 v[148:149], v187 offset:0x1800
	ds_read_b64_tr_b16 v[214:215], v187 offset:0x2000
	ds_read_b64_tr_b16 v[216:217], v187 offset:0x2800
	ds_read_b64_tr_b16 v[218:219], v187 offset:0x3000
	ds_read_b64_tr_b16 v[220:221], v187 offset:0x3800
	ds_read_b64_tr_b16 v[222:223], v187 offset:0x200
	ds_read_b64_tr_b16 v[224:225], v187 offset:0xa00
	ds_read_b64_tr_b16 v[226:227], v187 offset:0x1200
	ds_read_b64_tr_b16 v[228:229], v187 offset:0x1a00
	ds_read_b64_tr_b16 v[230:231], v187 offset:0x2200
	ds_read_b64_tr_b16 v[232:233], v187 offset:0x2a00
	ds_read_b64_tr_b16 v[234:235], v187 offset:0x3200
	ds_read_b64_tr_b16 v[236:237], v187 offset:0x3a00
	s_waitcnt lgkmcnt(8)
	s_waitcnt lgkmcnt(0)
	v_mfma_f32_32x32x16_bf16 v[114:129], v[154:157], v[12:15], v[114:129]
	v_mfma_f32_32x32x16_bf16 v[114:129], v[150:153], v[146:149], v[114:129]
	v_mfma_f32_32x32x16_bf16 v[114:129], v[8:11], v[214:217], v[114:129]
	v_mfma_f32_32x32x16_bf16 v[114:129], v[4:7], v[218:221], v[114:129]
	ds_read_b64_tr_b16 v[12:13], v187 offset:0x400
	ds_read_b64_tr_b16 v[14:15], v187 offset:0xc00
	ds_read_b64_tr_b16 v[146:147], v187 offset:0x1400
	ds_read_b64_tr_b16 v[148:149], v187 offset:0x1c00
	ds_read_b64_tr_b16 v[214:215], v187 offset:0x2400
	ds_read_b64_tr_b16 v[216:217], v187 offset:0x2c00
	ds_read_b64_tr_b16 v[218:219], v187 offset:0x3400
	ds_read_b64_tr_b16 v[220:221], v187 offset:0x3c00
	s_waitcnt lgkmcnt(8)
	v_mfma_f32_32x32x16_bf16 v[130:145], v[154:157], v[222:225], v[130:145]
	v_mfma_f32_32x32x16_bf16 v[130:145], v[150:153], v[226:229], v[130:145]
	v_mfma_f32_32x32x16_bf16 v[130:145], v[8:11], v[230:233], v[130:145]
	v_mfma_f32_32x32x16_bf16 v[130:145], v[4:7], v[234:237], v[130:145]
	ds_read_b64_tr_b16 v[222:223], v187 offset:0x600
	ds_read_b64_tr_b16 v[224:225], v187 offset:0xe00
	ds_read_b64_tr_b16 v[226:227], v187 offset:0x1600
	ds_read_b64_tr_b16 v[228:229], v187 offset:0x1e00
	ds_read_b64_tr_b16 v[230:231], v187 offset:0x2600
	ds_read_b64_tr_b16 v[232:233], v187 offset:0x2e00
	ds_read_b64_tr_b16 v[234:235], v187 offset:0x3600
	ds_read_b64_tr_b16 v[236:237], v187 offset:0x3e00
	s_waitcnt lgkmcnt(8)
	v_mfma_f32_32x32x16_bf16 v[82:97], v[154:157], v[12:15], v[82:97]
	v_mfma_f32_32x32x16_bf16 v[82:97], v[150:153], v[146:149], v[82:97]
	v_mfma_f32_32x32x16_bf16 v[82:97], v[8:11], v[214:217], v[82:97]
	v_mfma_f32_32x32x16_bf16 v[82:97], v[4:7], v[218:221], v[82:97]
	s_waitcnt lgkmcnt(0)
	v_mfma_f32_32x32x16_bf16 v[98:113], v[154:157], v[222:225], v[98:113]
	ds_read_b64_tr_b16 v[12:13], v188 offset:0
	ds_read_b64_tr_b16 v[14:15], v188 offset:0x800
	ds_read_b64_tr_b16 v[146:147], v188 offset:0x1000
	ds_read_b64_tr_b16 v[148:149], v188 offset:0x1800
	ds_read_b64_tr_b16 v[214:215], v188 offset:0x2000
	ds_read_b64_tr_b16 v[216:217], v188 offset:0x2800
	ds_read_b64_tr_b16 v[218:219], v188 offset:0x3000
	v_mfma_f32_32x32x16_bf16 v[98:113], v[150:153], v[226:229], v[98:113]
	ds_read_b64_tr_b16 v[220:221], v188 offset:0x3800
	v_mfma_f32_32x32x16_bf16 v[98:113], v[8:11], v[230:233], v[98:113]
	v_mfma_f32_32x32x16_bf16 v[98:113], v[4:7], v[234:237], v[98:113]
	ds_read_b64_tr_b16 v[222:223], v188 offset:0x200
	ds_read_b64_tr_b16 v[224:225], v188 offset:0xa00
	ds_read_b64_tr_b16 v[226:227], v188 offset:0x1200
	ds_read_b64_tr_b16 v[228:229], v188 offset:0x1a00
	ds_read_b64_tr_b16 v[230:231], v188 offset:0x2200
	ds_read_b64_tr_b16 v[232:233], v188 offset:0x2a00
	ds_read_b64_tr_b16 v[234:235], v188 offset:0x3200
	ds_read_b64_tr_b16 v[236:237], v188 offset:0x3a00
	s_waitcnt lgkmcnt(8)
	v_mfma_f32_32x32x16_bf16 v[50:65], v[154:157], v[12:15], v[50:65]
	v_mfma_f32_32x32x16_bf16 v[50:65], v[150:153], v[146:149], v[50:65]
	v_mfma_f32_32x32x16_bf16 v[50:65], v[8:11], v[214:217], v[50:65]
	v_mfma_f32_32x32x16_bf16 v[50:65], v[4:7], v[218:221], v[50:65]
	ds_read_b64_tr_b16 v[214:215], v188 offset:0x400
	ds_read_b64_tr_b16 v[216:217], v188 offset:0xc00
	ds_read_b64_tr_b16 v[218:219], v188 offset:0x1400
	ds_read_b64_tr_b16 v[220:221], v188 offset:0x1c00
	ds_read_b64_tr_b16 v[238:239], v188 offset:0x2400
	ds_read_b64_tr_b16 v[240:241], v188 offset:0x2c00
	ds_read_b64_tr_b16 v[242:243], v188 offset:0x3400
	ds_read_b64_tr_b16 v[244:245], v188 offset:0x3c00
	s_waitcnt lgkmcnt(8)
	v_mfma_f32_32x32x16_bf16 v[66:81], v[154:157], v[222:225], v[66:81]
	v_mfma_f32_32x32x16_bf16 v[66:81], v[150:153], v[226:229], v[66:81]
	v_mfma_f32_32x32x16_bf16 v[66:81], v[8:11], v[230:233], v[66:81]
	v_mfma_f32_32x32x16_bf16 v[66:81], v[4:7], v[234:237], v[66:81]
	ds_read_b64_tr_b16 v[222:223], v188 offset:0x600
	ds_read_b64_tr_b16 v[224:225], v188 offset:0xe00
	ds_read_b64_tr_b16 v[226:227], v188 offset:0x1600
	ds_read_b64_tr_b16 v[228:229], v188 offset:0x1e00
	ds_read_b64_tr_b16 v[146:147], v188 offset:0x2600
	ds_read_b64_tr_b16 v[148:149], v188 offset:0x2e00
	ds_read_b64_tr_b16 v[12:13], v188 offset:0x3600
	ds_read_b64_tr_b16 v[14:15], v188 offset:0x3e00
	s_waitcnt lgkmcnt(8)
	v_mfma_f32_32x32x16_bf16 v[18:33], v[154:157], v[214:217], v[18:33]
	v_mfma_f32_32x32x16_bf16 v[18:33], v[150:153], v[218:221], v[18:33]
	v_mfma_f32_32x32x16_bf16 v[18:33], v[8:11], v[238:241], v[18:33]
	v_mfma_f32_32x32x16_bf16 v[18:33], v[4:7], v[242:245], v[18:33]
	s_waitcnt lgkmcnt(0)
	v_add_u32_e32 v2, s18, v163
	ds_read_b128 v[214:217], v2 offset:128
	ds_read_b128 v[218:221], v2 offset:160
	v_mfma_f32_32x32x16_bf16 v[34:49], v[154:157], v[222:225], v[34:49]
	s_lshl_b32 s0, s21, 18
	s_add_u32 s0, s53, s0
	s_waitcnt lgkmcnt(0)
	v_rcp_f32_e32 v230, v214
	v_rcp_f32_e32 v231, v215
	v_rcp_f32_e32 v232, v216
	v_rcp_f32_e32 v224, v217
	v_rcp_f32_e32 v215, v218
	v_rcp_f32_e32 v214, v219
	ds_read_b128 v[216:219], v2 offset:192
	v_rcp_f32_e32 v183, v220
	v_rcp_f32_e32 v177, v221
	ds_read_b128 v[220:223], v2 offset:224
	v_lshlrev_b32_e32 v2, 1, v1
	v_mfma_f32_32x32x16_bf16 v[34:49], v[150:153], v[226:229], v[34:49]
	s_addc_u32 s1, s54, 0
	v_add3_u32 v151, s57, v165, v2
	v_lshlrev_b32_e32 v2, 1, v160
	s_waitcnt lgkmcnt(0)
	v_rcp_f32_e32 v175, v216
	v_rcp_f32_e32 v173, v217
	v_rcp_f32_e32 v157, v218
	v_add_u32_e32 v218, s57, v2
	v_lshl_add_u64 v[216:217], s[0:1], 0, v[2:3]
	v_mul_f32_e32 v2, v114, v230
	v_cvt_pk_bf16_f32 v2, v2, v2
	v_mul_f32_e32 v16, v130, v230
	ds_write_b16 v151, v2
	v_cvt_pk_bf16_f32 v2, v16, v16
	ds_write_b16 v151, v2 offset:64
	v_mul_f32_e32 v2, v115, v231
	v_cvt_pk_bf16_f32 v2, v2, v2
	v_mul_f32_e32 v16, v131, v231
	ds_write_b16 v151, v2 offset:128
	v_cvt_pk_bf16_f32 v2, v16, v16
	ds_write_b16 v151, v2 offset:192
	v_mul_f32_e32 v2, v116, v232
	v_cvt_pk_bf16_f32 v2, v2, v2
	v_mul_f32_e32 v16, v132, v232
	ds_write_b16 v151, v2 offset:256
	v_cvt_pk_bf16_f32 v2, v16, v16
	ds_write_b16 v151, v2 offset:320
	v_mul_f32_e32 v2, v117, v224
	v_cvt_pk_bf16_f32 v2, v2, v2
	v_mul_f32_e32 v16, v133, v224
	ds_write_b16 v151, v2 offset:384
	v_cvt_pk_bf16_f32 v2, v16, v16
	ds_write_b16 v151, v2 offset:448
	v_mul_f32_e32 v2, v118, v215
	v_cvt_pk_bf16_f32 v2, v2, v2
	v_mul_f32_e32 v16, v134, v215
	ds_write_b16 v151, v2 offset:1024
	v_cvt_pk_bf16_f32 v2, v16, v16
	ds_write_b16 v151, v2 offset:1088
	v_mul_f32_e32 v2, v119, v214
	v_cvt_pk_bf16_f32 v2, v2, v2
	v_mul_f32_e32 v16, v135, v214
	ds_write_b16 v151, v2 offset:1152
	v_cvt_pk_bf16_f32 v2, v16, v16
	ds_write_b16 v151, v2 offset:1216
	v_mul_f32_e32 v2, v120, v183
	v_cvt_pk_bf16_f32 v2, v2, v2
	v_mul_f32_e32 v16, v136, v183
	ds_write_b16 v151, v2 offset:1280
	v_cvt_pk_bf16_f32 v2, v16, v16
	ds_write_b16 v151, v2 offset:1344
	v_mul_f32_e32 v2, v121, v177
	v_cvt_pk_bf16_f32 v2, v2, v2
	v_mul_f32_e32 v16, v137, v177
	ds_write_b16 v151, v2 offset:1408
	v_cvt_pk_bf16_f32 v2, v16, v16
	ds_write_b16 v151, v2 offset:1472
	v_mul_f32_e32 v2, v122, v175
	v_cvt_pk_bf16_f32 v2, v2, v2
	v_mul_f32_e32 v16, v138, v175
	ds_write_b16 v151, v2 offset:2048
	v_cvt_pk_bf16_f32 v2, v16, v16
	ds_write_b16 v151, v2 offset:2112
	v_mul_f32_e32 v2, v123, v173
	v_cvt_pk_bf16_f32 v2, v2, v2
	v_rcp_f32_e32 v156, v219
	v_mul_f32_e32 v16, v139, v173
	ds_write_b16 v151, v2 offset:2176
	v_cvt_pk_bf16_f32 v2, v16, v16
	ds_write_b16 v151, v2 offset:2240
	v_mul_f32_e32 v2, v124, v157
	v_cvt_pk_bf16_f32 v2, v2, v2
	v_rcp_f32_e32 v155, v220
	v_mul_f32_e32 v16, v140, v157
	ds_write_b16 v151, v2 offset:2304
	v_cvt_pk_bf16_f32 v2, v16, v16
	ds_write_b16 v151, v2 offset:2368
	v_mul_f32_e32 v2, v125, v156
	v_cvt_pk_bf16_f32 v2, v2, v2
	v_rcp_f32_e32 v154, v221
	v_mul_f32_e32 v16, v141, v156
	ds_write_b16 v151, v2 offset:2432
	v_cvt_pk_bf16_f32 v2, v16, v16
	ds_write_b16 v151, v2 offset:2496
	v_mul_f32_e32 v2, v126, v155
	v_cvt_pk_bf16_f32 v2, v2, v2
	v_rcp_f32_e32 v153, v222
	v_mul_f32_e32 v16, v142, v155
	ds_write_b16 v151, v2 offset:3072
	v_cvt_pk_bf16_f32 v2, v16, v16
	ds_write_b16 v151, v2 offset:3136
	v_mul_f32_e32 v2, v127, v154
	v_cvt_pk_bf16_f32 v2, v2, v2
	v_rcp_f32_e32 v150, v223
	v_mul_f32_e32 v16, v143, v154
	ds_write_b16 v151, v2 offset:3200
	v_cvt_pk_bf16_f32 v2, v16, v16
	ds_write_b16 v151, v2 offset:3264
	v_mul_f32_e32 v2, v128, v153
	v_cvt_pk_bf16_f32 v2, v2, v2
	v_mul_f32_e32 v16, v144, v153
	ds_write_b16 v151, v2 offset:3328
	v_cvt_pk_bf16_f32 v2, v16, v16
	ds_write_b16 v151, v2 offset:3392
	v_mul_f32_e32 v2, v129, v150
	v_cvt_pk_bf16_f32 v2, v2, v2
	v_mul_f32_e32 v16, v145, v150
	ds_write_b16 v151, v2 offset:3456
	v_cvt_pk_bf16_f32 v2, v16, v16
	ds_write_b16 v151, v2 offset:3520
	v_add_u32_e32 v152, v218, v167
	s_waitcnt lgkmcnt(0)
	ds_read_b128 v[114:117], v152
	v_add_u32_e32 v126, v218, v171
	ds_read_b128 v[118:121], v126
	v_lshlrev_b32_e32 v2, 1, v162
	v_lshl_add_u64 v[16:17], v[216:217], 0, v[2:3]
	v_lshlrev_b32_e32 v2, 1, v166
	s_waitcnt lgkmcnt(0)
	global_store_dwordx4 v[16:17], v[114:117], off
	v_add_u32_e32 v127, v218, v179
	v_add_u32_e32 v128, v218, v181
	v_lshl_add_u64 v[114:115], v[216:217], 0, v[2:3]
	ds_read_b128 v[122:125], v128
	global_store_dwordx4 v[114:115], v[118:121], off
	ds_read_b128 v[118:121], v127
	v_lshlrev_b32_e32 v2, 1, v168
	v_lshl_add_u64 v[116:117], v[216:217], 0, v[2:3]
	v_lshlrev_b32_e32 v2, 1, v170
	v_mfma_f32_32x32x16_bf16 v[34:49], v[8:11], v[146:149], v[34:49]
	s_waitcnt lgkmcnt(0)
	global_store_dwordx4 v[116:117], v[118:121], off
	v_mul_f32_e32 v8, v66, v230
	s_mov_b64 s[0:1], 0
	v_lshl_add_u64 v[118:119], v[216:217], 0, v[2:3]
	global_store_dwordx4 v[118:119], v[122:125], off
	v_mul_f32_e32 v2, v82, v230
	s_waitcnt lgkmcnt(0)
	v_cvt_pk_bf16_f32 v2, v2, v2
	v_mul_f32_e32 v82, v98, v230
	ds_write_b16 v151, v2
	v_cvt_pk_bf16_f32 v2, v82, v82
	ds_write_b16 v151, v2 offset:64
	v_mul_f32_e32 v2, v83, v231
	v_cvt_pk_bf16_f32 v2, v2, v2
	v_mul_f32_e32 v82, v99, v231
	ds_write_b16 v151, v2 offset:128
	v_cvt_pk_bf16_f32 v2, v82, v82
	ds_write_b16 v151, v2 offset:192
	v_mul_f32_e32 v2, v84, v232
	v_cvt_pk_bf16_f32 v2, v2, v2
	v_mul_f32_e32 v82, v100, v232
	ds_write_b16 v151, v2 offset:256
	v_cvt_pk_bf16_f32 v2, v82, v82
	ds_write_b16 v151, v2 offset:320
	v_mul_f32_e32 v2, v85, v224
	v_cvt_pk_bf16_f32 v2, v2, v2
	v_mul_f32_e32 v82, v101, v224
	ds_write_b16 v151, v2 offset:384
	v_cvt_pk_bf16_f32 v2, v82, v82
	ds_write_b16 v151, v2 offset:448
	v_mul_f32_e32 v2, v86, v215
	v_cvt_pk_bf16_f32 v2, v2, v2
	v_mul_f32_e32 v82, v102, v215
	ds_write_b16 v151, v2 offset:1024
	v_cvt_pk_bf16_f32 v2, v82, v82
	ds_write_b16 v151, v2 offset:1088
	v_mul_f32_e32 v2, v87, v214
	v_cvt_pk_bf16_f32 v2, v2, v2
	v_mul_f32_e32 v82, v103, v214
	ds_write_b16 v151, v2 offset:1152
	v_cvt_pk_bf16_f32 v2, v82, v82
	ds_write_b16 v151, v2 offset:1216
	v_mul_f32_e32 v2, v88, v183
	v_cvt_pk_bf16_f32 v2, v2, v2
	v_mul_f32_e32 v82, v104, v183
	ds_write_b16 v151, v2 offset:1280
	v_cvt_pk_bf16_f32 v2, v82, v82
	ds_write_b16 v151, v2 offset:1344
	v_mul_f32_e32 v2, v89, v177
	v_cvt_pk_bf16_f32 v2, v2, v2
	v_mul_f32_e32 v82, v105, v177
	ds_write_b16 v151, v2 offset:1408
	v_cvt_pk_bf16_f32 v2, v82, v82
	ds_write_b16 v151, v2 offset:1472
	v_mul_f32_e32 v2, v90, v175
	v_cvt_pk_bf16_f32 v2, v2, v2
	v_mul_f32_e32 v82, v106, v175
	ds_write_b16 v151, v2 offset:2048
	v_cvt_pk_bf16_f32 v2, v82, v82
	ds_write_b16 v151, v2 offset:2112
	v_mul_f32_e32 v2, v91, v173
	v_cvt_pk_bf16_f32 v2, v2, v2
	v_mul_f32_e32 v82, v107, v173
	ds_write_b16 v151, v2 offset:2176
	v_cvt_pk_bf16_f32 v2, v82, v82
	ds_write_b16 v151, v2 offset:2240
	v_mul_f32_e32 v2, v92, v157
	v_cvt_pk_bf16_f32 v2, v2, v2
	v_mul_f32_e32 v82, v108, v157
	ds_write_b16 v151, v2 offset:2304
	v_cvt_pk_bf16_f32 v2, v82, v82
	ds_write_b16 v151, v2 offset:2368
	v_mul_f32_e32 v2, v93, v156
	v_cvt_pk_bf16_f32 v2, v2, v2
	v_mul_f32_e32 v82, v109, v156
	ds_write_b16 v151, v2 offset:2432
	v_cvt_pk_bf16_f32 v2, v82, v82
	ds_write_b16 v151, v2 offset:2496
	v_mul_f32_e32 v2, v94, v155
	v_cvt_pk_bf16_f32 v2, v2, v2
	v_mul_f32_e32 v82, v110, v155
	ds_write_b16 v151, v2 offset:3072
	v_cvt_pk_bf16_f32 v2, v82, v82
	ds_write_b16 v151, v2 offset:3136
	v_mul_f32_e32 v2, v95, v154
	v_cvt_pk_bf16_f32 v2, v2, v2
	v_mul_f32_e32 v82, v111, v154
	ds_write_b16 v151, v2 offset:3200
	v_cvt_pk_bf16_f32 v2, v82, v82
	ds_write_b16 v151, v2 offset:3264
	v_mul_f32_e32 v2, v96, v153
	v_cvt_pk_bf16_f32 v2, v2, v2
	v_mul_f32_e32 v82, v112, v153
	ds_write_b16 v151, v2 offset:3328
	v_cvt_pk_bf16_f32 v2, v82, v82
	ds_write_b16 v151, v2 offset:3392
	v_mul_f32_e32 v2, v97, v150
	v_cvt_pk_bf16_f32 v2, v2, v2
	v_mul_f32_e32 v82, v113, v150
	ds_write_b16 v151, v2 offset:3456
	v_cvt_pk_bf16_f32 v2, v82, v82
	ds_write_b16 v151, v2 offset:3520
	s_waitcnt lgkmcnt(0)
	ds_read_b128 v[82:85], v152
	ds_read_b128 v[86:89], v126
	ds_read_b128 v[90:93], v127
	ds_read_b128 v[94:97], v128
	s_waitcnt lgkmcnt(0)
	global_store_dwordx4 v[16:17], v[82:85], off offset:128
	global_store_dwordx4 v[114:115], v[86:89], off offset:128
	global_store_dwordx4 v[116:117], v[90:93], off offset:128
	global_store_dwordx4 v[118:119], v[94:97], off offset:128
	v_mul_f32_e32 v2, v50, v230
	s_waitcnt lgkmcnt(0)
	v_cvt_pk_bf16_f32 v2, v2, v2
	ds_write_b16 v151, v2
	v_cvt_pk_bf16_f32 v2, v8, v8
	ds_write_b16 v151, v2 offset:64
	v_mul_f32_e32 v2, v51, v231
	v_cvt_pk_bf16_f32 v2, v2, v2
	v_mul_f32_e32 v8, v67, v231
	ds_write_b16 v151, v2 offset:128
	v_cvt_pk_bf16_f32 v2, v8, v8
	ds_write_b16 v151, v2 offset:192
	v_mul_f32_e32 v2, v52, v232
	v_cvt_pk_bf16_f32 v2, v2, v2
	v_mul_f32_e32 v8, v68, v232
	ds_write_b16 v151, v2 offset:256
	v_cvt_pk_bf16_f32 v2, v8, v8
	ds_write_b16 v151, v2 offset:320
	v_mul_f32_e32 v2, v53, v224
	v_cvt_pk_bf16_f32 v2, v2, v2
	v_mul_f32_e32 v8, v69, v224
	ds_write_b16 v151, v2 offset:384
	v_cvt_pk_bf16_f32 v2, v8, v8
	ds_write_b16 v151, v2 offset:448
	v_mul_f32_e32 v2, v54, v215
	v_cvt_pk_bf16_f32 v2, v2, v2
	v_mul_f32_e32 v8, v70, v215
	ds_write_b16 v151, v2 offset:1024
	v_cvt_pk_bf16_f32 v2, v8, v8
	ds_write_b16 v151, v2 offset:1088
	v_mul_f32_e32 v2, v55, v214
	v_cvt_pk_bf16_f32 v2, v2, v2
	v_mul_f32_e32 v8, v71, v214
	ds_write_b16 v151, v2 offset:1152
	v_cvt_pk_bf16_f32 v2, v8, v8
	ds_write_b16 v151, v2 offset:1216
	v_mul_f32_e32 v2, v56, v183
	v_cvt_pk_bf16_f32 v2, v2, v2
	v_mul_f32_e32 v8, v72, v183
	ds_write_b16 v151, v2 offset:1280
	v_cvt_pk_bf16_f32 v2, v8, v8
	ds_write_b16 v151, v2 offset:1344
	v_mul_f32_e32 v2, v57, v177
	v_cvt_pk_bf16_f32 v2, v2, v2
	v_mul_f32_e32 v8, v73, v177
	ds_write_b16 v151, v2 offset:1408
	v_cvt_pk_bf16_f32 v2, v8, v8
	ds_write_b16 v151, v2 offset:1472
	v_mul_f32_e32 v2, v58, v175
	v_cvt_pk_bf16_f32 v2, v2, v2
	v_mul_f32_e32 v8, v74, v175
	ds_write_b16 v151, v2 offset:2048
	v_cvt_pk_bf16_f32 v2, v8, v8
	ds_write_b16 v151, v2 offset:2112
	v_mul_f32_e32 v2, v59, v173
	v_cvt_pk_bf16_f32 v2, v2, v2
	v_mul_f32_e32 v8, v75, v173
	ds_write_b16 v151, v2 offset:2176
	v_cvt_pk_bf16_f32 v2, v8, v8
	ds_write_b16 v151, v2 offset:2240
	v_mul_f32_e32 v2, v60, v157
	v_cvt_pk_bf16_f32 v2, v2, v2
	v_mul_f32_e32 v8, v76, v157
	ds_write_b16 v151, v2 offset:2304
	v_cvt_pk_bf16_f32 v2, v8, v8
	ds_write_b16 v151, v2 offset:2368
	v_mul_f32_e32 v2, v61, v156
	v_cvt_pk_bf16_f32 v2, v2, v2
	v_mul_f32_e32 v8, v77, v156
	ds_write_b16 v151, v2 offset:2432
	v_cvt_pk_bf16_f32 v2, v8, v8
	ds_write_b16 v151, v2 offset:2496
	v_mul_f32_e32 v2, v62, v155
	v_cvt_pk_bf16_f32 v2, v2, v2
	v_mul_f32_e32 v8, v78, v155
	ds_write_b16 v151, v2 offset:3072
	v_cvt_pk_bf16_f32 v2, v8, v8
	ds_write_b16 v151, v2 offset:3136
	v_mul_f32_e32 v2, v63, v154
	v_cvt_pk_bf16_f32 v2, v2, v2
	v_mul_f32_e32 v8, v79, v154
	ds_write_b16 v151, v2 offset:3200
	v_cvt_pk_bf16_f32 v2, v8, v8
	ds_write_b16 v151, v2 offset:3264
	v_mul_f32_e32 v2, v64, v153
	v_cvt_pk_bf16_f32 v2, v2, v2
	v_mul_f32_e32 v8, v80, v153
	ds_write_b16 v151, v2 offset:3328
	v_cvt_pk_bf16_f32 v2, v8, v8
	ds_write_b16 v151, v2 offset:3392
	v_mul_f32_e32 v2, v65, v150
	v_cvt_pk_bf16_f32 v2, v2, v2
	v_mul_f32_e32 v8, v81, v150
	ds_write_b16 v151, v2 offset:3456
	v_cvt_pk_bf16_f32 v2, v8, v8
	ds_write_b16 v151, v2 offset:3520
	s_waitcnt lgkmcnt(0)
	v_mfma_f32_32x32x16_bf16 v[34:49], v[4:7], v[12:15], v[34:49]
	ds_read_b128 v[8:11], v152
	ds_read_b128 v[50:53], v126
	ds_read_b128 v[54:57], v127
	ds_read_b128 v[58:61], v128
	s_waitcnt lgkmcnt(0)
	global_store_dwordx4 v[16:17], v[8:11], off offset:256
	global_store_dwordx4 v[114:115], v[50:53], off offset:256
	global_store_dwordx4 v[116:117], v[54:57], off offset:256
	global_store_dwordx4 v[118:119], v[58:61], off offset:256
	v_mul_f32_e32 v2, v18, v230
	s_waitcnt lgkmcnt(0)
	v_cvt_pk_bf16_f32 v2, v2, v2
	s_nop 1
	v_mul_f32_e32 v4, v34, v230
	ds_write_b16 v151, v2
	v_cvt_pk_bf16_f32 v2, v4, v4
	ds_write_b16 v151, v2 offset:64
	v_mul_f32_e32 v2, v19, v231
	v_cvt_pk_bf16_f32 v2, v2, v2
	v_mul_f32_e32 v4, v35, v231
	ds_write_b16 v151, v2 offset:128
	v_cvt_pk_bf16_f32 v2, v4, v4
	ds_write_b16 v151, v2 offset:192
	v_mul_f32_e32 v2, v20, v232
	v_cvt_pk_bf16_f32 v2, v2, v2
	v_mul_f32_e32 v4, v36, v232
	ds_write_b16 v151, v2 offset:256
	v_cvt_pk_bf16_f32 v2, v4, v4
	ds_write_b16 v151, v2 offset:320
	v_mul_f32_e32 v2, v21, v224
	v_cvt_pk_bf16_f32 v2, v2, v2
	v_mul_f32_e32 v4, v37, v224
	ds_write_b16 v151, v2 offset:384
	v_cvt_pk_bf16_f32 v2, v4, v4
	ds_write_b16 v151, v2 offset:448
	v_mul_f32_e32 v2, v22, v215
	v_cvt_pk_bf16_f32 v2, v2, v2
	v_mul_f32_e32 v4, v38, v215
	ds_write_b16 v151, v2 offset:1024
	v_cvt_pk_bf16_f32 v2, v4, v4
	ds_write_b16 v151, v2 offset:1088
	v_mul_f32_e32 v2, v23, v214
	v_cvt_pk_bf16_f32 v2, v2, v2
	v_mul_f32_e32 v4, v39, v214
	ds_write_b16 v151, v2 offset:1152
	v_cvt_pk_bf16_f32 v2, v4, v4
	ds_write_b16 v151, v2 offset:1216
	v_mul_f32_e32 v2, v24, v183
	v_cvt_pk_bf16_f32 v2, v2, v2
	v_mul_f32_e32 v4, v40, v183
	ds_write_b16 v151, v2 offset:1280
	v_cvt_pk_bf16_f32 v2, v4, v4
	ds_write_b16 v151, v2 offset:1344
	v_mul_f32_e32 v2, v25, v177
	v_cvt_pk_bf16_f32 v2, v2, v2
	v_mul_f32_e32 v4, v41, v177
	ds_write_b16 v151, v2 offset:1408
	v_cvt_pk_bf16_f32 v2, v4, v4
	ds_write_b16 v151, v2 offset:1472
	v_mul_f32_e32 v2, v26, v175
	v_cvt_pk_bf16_f32 v2, v2, v2
	v_mul_f32_e32 v4, v42, v175
	ds_write_b16 v151, v2 offset:2048
	v_cvt_pk_bf16_f32 v2, v4, v4
	ds_write_b16 v151, v2 offset:2112
	v_mul_f32_e32 v2, v27, v173
	v_cvt_pk_bf16_f32 v2, v2, v2
	v_mul_f32_e32 v4, v43, v173
	ds_write_b16 v151, v2 offset:2176
	v_cvt_pk_bf16_f32 v2, v4, v4
	ds_write_b16 v151, v2 offset:2240
	v_mul_f32_e32 v2, v28, v157
	v_cvt_pk_bf16_f32 v2, v2, v2
	v_mul_f32_e32 v4, v44, v157
	ds_write_b16 v151, v2 offset:2304
	v_cvt_pk_bf16_f32 v2, v4, v4
	ds_write_b16 v151, v2 offset:2368
	v_mul_f32_e32 v2, v29, v156
	v_cvt_pk_bf16_f32 v2, v2, v2
	v_mul_f32_e32 v4, v45, v156
	ds_write_b16 v151, v2 offset:2432
	v_cvt_pk_bf16_f32 v2, v4, v4
	ds_write_b16 v151, v2 offset:2496
	v_mul_f32_e32 v2, v30, v155
	v_cvt_pk_bf16_f32 v2, v2, v2
	v_mul_f32_e32 v4, v46, v155
	ds_write_b16 v151, v2 offset:3072
	v_cvt_pk_bf16_f32 v2, v4, v4
	ds_write_b16 v151, v2 offset:3136
	v_mul_f32_e32 v2, v31, v154
	v_cvt_pk_bf16_f32 v2, v2, v2
	v_mul_f32_e32 v4, v47, v154
	ds_write_b16 v151, v2 offset:3200
	v_cvt_pk_bf16_f32 v2, v4, v4
	ds_write_b16 v151, v2 offset:3264
	v_mul_f32_e32 v2, v32, v153
	v_cvt_pk_bf16_f32 v2, v2, v2
	v_mul_f32_e32 v4, v48, v153
	ds_write_b16 v151, v2 offset:3328
	v_cvt_pk_bf16_f32 v2, v4, v4
	ds_write_b16 v151, v2 offset:3392
	v_mul_f32_e32 v2, v33, v150
	v_cvt_pk_bf16_f32 v2, v2, v2
	v_mul_f32_e32 v4, v49, v150
	ds_write_b16 v151, v2 offset:3456
	v_cvt_pk_bf16_f32 v2, v4, v4
	ds_write_b16 v151, v2 offset:3520
	s_waitcnt lgkmcnt(0)
	ds_read_b128 v[4:7], v152
	ds_read_b128 v[8:11], v126
	ds_read_b128 v[12:15], v127
	ds_read_b128 v[18:21], v128
	s_waitcnt lgkmcnt(0)
	global_store_dwordx4 v[16:17], v[4:7], off offset:384
	global_store_dwordx4 v[114:115], v[8:11], off offset:384
	global_store_dwordx4 v[116:117], v[12:15], off offset:384
	global_store_dwordx4 v[118:119], v[18:21], off offset:384
	s_waitcnt lgkmcnt(0)
	s_waitcnt lgkmcnt(0)
	s_barrier

.LBB0_1385:
	s_add_i32 s6, s6, 64
	s_add_i32 s66, s66, 0x8000
	s_cmp_eq_u32 s63, s66
	s_cbranch_scc1 .Lrotv_exit_1
	s_waitcnt vmcnt(0)
	s_waitcnt lgkmcnt(0)
	s_barrier
.LBB0_1386:
	v_mov_b32_e32 v2, v178
	s_ashr_i32 s7, s6, 31
	v_lshrrev_b32_e32 v5, 1, v2
	v_bfe_u32 v4, v2, 2, 2
	v_and_b32_e32 v5, 8, v5
	v_or3_b32 v4, v4, v5, s60
	v_and_b32_e32 v5, 0xffffffe0, v2
	s_lshl_b64 s[68:69], s[6:7], 9
	v_lshlrev_b32_e32 v2, 3, v2
	v_add_u32_e32 v5, s62, v5
	s_add_u32 s68, s55, s68
	v_and_or_b32 v2, v2, 24, v5
	s_addc_u32 s69, s56, s69
	s_and_b32 s7, s66, 0x8000
	v_lshl_add_u32 v4, v4, 8, v2
	s_add_i32 s67, s15, s7
	v_ashrrev_i32_e32 v5, 31, v4
	s_add_i32 s70, s67, 0x4000
	v_lshl_add_u64 v[6:7], v[4:5], 1, s[68:69]
	s_mov_b32 m0, s67
	v_add_u32_e32 v2, s18, v161
	global_load_lds_dwordx4 v[6:7], off
	v_lshl_add_u64 v[6:7], v[6:7], 0, s[12:13]
	s_mov_b32 m0, s70
	s_xor_b32 s7, s7, 0x8000
	global_load_lds_dwordx4 v[6:7], off
	v_add_u32_e32 v6, 0x1000, v4
	v_ashrrev_i32_e32 v7, 31, v6
	v_lshl_add_u64 v[6:7], v[6:7], 1, s[68:69]
	s_add_i32 m0, s67, 0x1000
	v_add_u32_e32 v16, s7, v185
	global_load_lds_dwordx4 v[6:7], off
	v_lshl_add_u64 v[6:7], v[6:7], 0, s[12:13]
	s_add_i32 m0, s67, 0x5000
	s_nop 0
	global_load_lds_dwordx4 v[6:7], off
	v_add_u32_e32 v6, 0x2000, v4
	v_ashrrev_i32_e32 v7, 31, v6
	v_lshl_add_u64 v[6:7], v[6:7], 1, s[68:69]
	s_add_i32 m0, s67, 0x2000
	v_add_u32_e32 v4, 0x3000, v4
	global_load_lds_dwordx4 v[6:7], off
	v_lshl_add_u64 v[6:7], v[6:7], 0, s[12:13]
	s_add_i32 m0, s67, 0x6000
	v_ashrrev_i32_e32 v5, 31, v4
	global_load_lds_dwordx4 v[6:7], off
	v_lshl_add_u64 v[4:5], v[4:5], 1, s[68:69]
	s_add_i32 m0, s67, 0x3000
	s_nop 0
	global_load_lds_dwordx4 v[4:5], off
	v_lshl_add_u64 v[4:5], v[4:5], 0, s[12:13]
	s_add_i32 m0, s67, 0x7000
	s_nop 0
	global_load_lds_dwordx4 v[4:5], off
	ds_read_b128 v[146:149], v2
	ds_read_b128 v[12:15], v2 offset:1024
	ds_read_b128 v[8:11], v2 offset:2048
	ds_read_b128 v[4:7], v2 offset:3072
	s_waitcnt lgkmcnt(0)
	ds_read_b64_tr_b16 v[150:151], v16 offset:0
	ds_read_b64_tr_b16 v[152:153], v16 offset:0x800
	ds_read_b64_tr_b16 v[214:215], v16 offset:0x1000
	ds_read_b64_tr_b16 v[216:217], v16 offset:0x1800
	ds_read_b64_tr_b16 v[218:219], v16 offset:0x2000
	ds_read_b64_tr_b16 v[220:221], v16 offset:0x2800
	ds_read_b64_tr_b16 v[222:223], v16 offset:0x3000
	ds_read_b64_tr_b16 v[224:225], v16 offset:0x3800
	ds_read_b64_tr_b16 v[226:227], v16 offset:0x200
	ds_read_b64_tr_b16 v[228:229], v16 offset:0xa00
	ds_read_b64_tr_b16 v[230:231], v16 offset:0x1200
	ds_read_b64_tr_b16 v[232:233], v16 offset:0x1a00
	ds_read_b64_tr_b16 v[234:235], v16 offset:0x2200
	ds_read_b64_tr_b16 v[236:237], v16 offset:0x2a00
	ds_read_b64_tr_b16 v[238:239], v16 offset:0x3200
	ds_read_b64_tr_b16 v[240:241], v16 offset:0x3a00
	s_waitcnt lgkmcnt(8)
	s_waitcnt lgkmcnt(0)
	v_mfma_f32_32x32x16_bf16 v[114:129], v[146:149], v[150:153], v[114:129]
	v_mfma_f32_32x32x16_bf16 v[114:129], v[12:15], v[214:217], v[114:129]
	v_mfma_f32_32x32x16_bf16 v[114:129], v[8:11], v[218:221], v[114:129]
	v_mfma_f32_32x32x16_bf16 v[114:129], v[4:7], v[222:225], v[114:129]
	ds_read_b64_tr_b16 v[150:151], v16 offset:0x400
	ds_read_b64_tr_b16 v[152:153], v16 offset:0xc00
	ds_read_b64_tr_b16 v[214:215], v16 offset:0x1400
	ds_read_b64_tr_b16 v[216:217], v16 offset:0x1c00
	ds_read_b64_tr_b16 v[218:219], v16 offset:0x2400
	ds_read_b64_tr_b16 v[220:221], v16 offset:0x2c00
	ds_read_b64_tr_b16 v[222:223], v16 offset:0x3400
	ds_read_b64_tr_b16 v[224:225], v16 offset:0x3c00
	s_waitcnt lgkmcnt(8)
	v_mfma_f32_32x32x16_bf16 v[130:145], v[146:149], v[226:229], v[130:145]
	v_mfma_f32_32x32x16_bf16 v[130:145], v[12:15], v[230:233], v[130:145]
	v_mfma_f32_32x32x16_bf16 v[130:145], v[8:11], v[234:237], v[130:145]
	v_mfma_f32_32x32x16_bf16 v[130:145], v[4:7], v[238:241], v[130:145]
	ds_read_b64_tr_b16 v[226:227], v16 offset:0x600
	ds_read_b64_tr_b16 v[228:229], v16 offset:0xe00
	ds_read_b64_tr_b16 v[230:231], v16 offset:0x1600
	ds_read_b64_tr_b16 v[232:233], v16 offset:0x1e00
	ds_read_b64_tr_b16 v[234:235], v16 offset:0x2600
	ds_read_b64_tr_b16 v[236:237], v16 offset:0x2e00
	ds_read_b64_tr_b16 v[238:239], v16 offset:0x3600
	ds_read_b64_tr_b16 v[240:241], v16 offset:0x3e00
	s_waitcnt lgkmcnt(8)
	v_mfma_f32_32x32x16_bf16 v[82:97], v[146:149], v[150:153], v[82:97]
	v_mfma_f32_32x32x16_bf16 v[82:97], v[12:15], v[214:217], v[82:97]
	v_mfma_f32_32x32x16_bf16 v[82:97], v[8:11], v[218:221], v[82:97]
	v_mfma_f32_32x32x16_bf16 v[82:97], v[4:7], v[222:225], v[82:97]
	s_waitcnt lgkmcnt(0)
	v_mfma_f32_32x32x16_bf16 v[98:113], v[146:149], v[226:229], v[98:113]
	s_waitcnt lgkmcnt(0)
	s_barrier
	v_add_u32_e32 v16, 0x4000, v16
	ds_read_b64_tr_b16 v[150:151], v16 offset:0
	ds_read_b64_tr_b16 v[152:153], v16 offset:0x800
	ds_read_b64_tr_b16 v[214:215], v16 offset:0x1000
	ds_read_b64_tr_b16 v[216:217], v16 offset:0x1800
	ds_read_b64_tr_b16 v[218:219], v16 offset:0x2000
	v_mfma_f32_32x32x16_bf16 v[98:113], v[12:15], v[230:233], v[98:113]
	ds_read_b64_tr_b16 v[220:221], v16 offset:0x2800
	ds_read_b64_tr_b16 v[222:223], v16 offset:0x3000
	ds_read_b64_tr_b16 v[224:225], v16 offset:0x3800
	v_mfma_f32_32x32x16_bf16 v[98:113], v[8:11], v[234:237], v[98:113]
	v_mfma_f32_32x32x16_bf16 v[98:113], v[4:7], v[238:241], v[98:113]
	ds_read_b64_tr_b16 v[226:227], v16 offset:0x200
	ds_read_b64_tr_b16 v[228:229], v16 offset:0xa00
	ds_read_b64_tr_b16 v[230:231], v16 offset:0x1200
	ds_read_b64_tr_b16 v[232:233], v16 offset:0x1a00
	ds_read_b64_tr_b16 v[234:235], v16 offset:0x2200
	ds_read_b64_tr_b16 v[236:237], v16 offset:0x2a00
	ds_read_b64_tr_b16 v[238:239], v16 offset:0x3200
	ds_read_b64_tr_b16 v[240:241], v16 offset:0x3a00
	s_waitcnt lgkmcnt(8)
	v_mfma_f32_32x32x16_bf16 v[50:65], v[146:149], v[150:153], v[50:65]
	v_mfma_f32_32x32x16_bf16 v[50:65], v[12:15], v[214:217], v[50:65]
	v_mfma_f32_32x32x16_bf16 v[50:65], v[8:11], v[218:221], v[50:65]
	v_mfma_f32_32x32x16_bf16 v[50:65], v[4:7], v[222:225], v[50:65]
	ds_read_b64_tr_b16 v[150:151], v16 offset:0x400
	ds_read_b64_tr_b16 v[152:153], v16 offset:0xc00
	ds_read_b64_tr_b16 v[214:215], v16 offset:0x1400
	ds_read_b64_tr_b16 v[216:217], v16 offset:0x1c00
	ds_read_b64_tr_b16 v[218:219], v16 offset:0x2400
	ds_read_b64_tr_b16 v[220:221], v16 offset:0x2c00
	ds_read_b64_tr_b16 v[222:223], v16 offset:0x3400
	ds_read_b64_tr_b16 v[224:225], v16 offset:0x3c00
	s_waitcnt lgkmcnt(8)
	v_mfma_f32_32x32x16_bf16 v[66:81], v[146:149], v[226:229], v[66:81]
	v_mfma_f32_32x32x16_bf16 v[66:81], v[12:15], v[230:233], v[66:81]
	v_mfma_f32_32x32x16_bf16 v[66:81], v[8:11], v[234:237], v[66:81]
	v_mfma_f32_32x32x16_bf16 v[66:81], v[4:7], v[238:241], v[66:81]
	ds_read_b64_tr_b16 v[226:227], v16 offset:0x600
	ds_read_b64_tr_b16 v[228:229], v16 offset:0xe00
	ds_read_b64_tr_b16 v[230:231], v16 offset:0x1600
	ds_read_b64_tr_b16 v[232:233], v16 offset:0x1e00
	ds_read_b64_tr_b16 v[234:235], v16 offset:0x2600
	ds_read_b64_tr_b16 v[236:237], v16 offset:0x2e00
	ds_read_b64_tr_b16 v[238:239], v16 offset:0x3600
	ds_read_b64_tr_b16 v[240:241], v16 offset:0x3e00
	s_waitcnt lgkmcnt(8)
	v_mfma_f32_32x32x16_bf16 v[18:33], v[146:149], v[150:153], v[18:33]
	v_mfma_f32_32x32x16_bf16 v[18:33], v[12:15], v[214:217], v[18:33]
	v_mfma_f32_32x32x16_bf16 v[18:33], v[8:11], v[218:221], v[18:33]
	v_mfma_f32_32x32x16_bf16 v[18:33], v[4:7], v[222:225], v[18:33]
	s_waitcnt lgkmcnt(0)
	v_mfma_f32_32x32x16_bf16 v[34:49], v[146:149], v[226:229], v[34:49]
	s_add_i32 s7, s19, 0
	s_add_i32 s7, s7, 0x20000
	v_mfma_f32_32x32x16_bf16 v[34:49], v[12:15], v[230:233], v[34:49]
	v_mfma_f32_32x32x16_bf16 v[34:49], v[8:11], v[234:237], v[34:49]
	v_mov_b32_e32 v8, s7
	ds_read_b32 v8, v8
	s_waitcnt lgkmcnt(0)
	v_readfirstlane_b32 s7, v8
	v_mfma_f32_32x32x16_bf16 v[34:49], v[4:7], v[238:241], v[34:49]
	s_cmp_eq_u32 s7, 0
	s_cbranch_scc1 .LBB0_1385
	v_add_u32_e32 v4, s20, v163
	ds_read_b128 v[146:149], v4 offset:96
	ds_read_b128 v[12:15], v4 offset:64
	ds_read_b128 v[8:11], v4 offset:32
	ds_read_b128 v[4:7], v4
	s_waitcnt lgkmcnt(0)
	v_pk_mul_f32 v[126:127], v[126:127], v[146:147]
	v_pk_mul_f32 v[122:123], v[122:123], v[12:13]
	v_pk_mul_f32 v[118:119], v[118:119], v[8:9]
	v_pk_mul_f32 v[128:129], v[128:129], v[148:149]
	v_pk_mul_f32 v[124:125], v[124:125], v[14:15]
	v_pk_mul_f32 v[120:121], v[120:121], v[10:11]
	v_pk_mul_f32 v[116:117], v[116:117], v[6:7]
	v_pk_mul_f32 v[114:115], v[114:115], v[4:5]
	v_pk_mul_f32 v[142:143], v[142:143], v[146:147]
	v_pk_mul_f32 v[138:139], v[138:139], v[12:13]
	v_pk_mul_f32 v[134:135], v[134:135], v[8:9]
	v_pk_mul_f32 v[144:145], v[144:145], v[148:149]
	v_pk_mul_f32 v[140:141], v[140:141], v[14:15]
	v_pk_mul_f32 v[136:137], v[136:137], v[10:11]
	v_pk_mul_f32 v[132:133], v[132:133], v[6:7]
	v_pk_mul_f32 v[130:131], v[130:131], v[4:5]
	v_pk_mul_f32 v[94:95], v[94:95], v[146:147]
	v_pk_mul_f32 v[90:91], v[90:91], v[12:13]
	v_pk_mul_f32 v[86:87], v[86:87], v[8:9]
	v_pk_mul_f32 v[96:97], v[96:97], v[148:149]
	v_pk_mul_f32 v[92:93], v[92:93], v[14:15]
	v_pk_mul_f32 v[88:89], v[88:89], v[10:11]
	v_pk_mul_f32 v[84:85], v[84:85], v[6:7]
	v_pk_mul_f32 v[82:83], v[82:83], v[4:5]
	v_pk_mul_f32 v[110:111], v[110:111], v[146:147]
	v_pk_mul_f32 v[106:107], v[106:107], v[12:13]
	v_pk_mul_f32 v[102:103], v[102:103], v[8:9]
	v_pk_mul_f32 v[112:113], v[112:113], v[148:149]
	v_pk_mul_f32 v[108:109], v[108:109], v[14:15]
	v_pk_mul_f32 v[104:105], v[104:105], v[10:11]
	v_pk_mul_f32 v[100:101], v[100:101], v[6:7]
	v_pk_mul_f32 v[98:99], v[98:99], v[4:5]
	v_pk_mul_f32 v[62:63], v[62:63], v[146:147]
	v_pk_mul_f32 v[58:59], v[58:59], v[12:13]
	v_pk_mul_f32 v[54:55], v[54:55], v[8:9]
	v_pk_mul_f32 v[64:65], v[64:65], v[148:149]
	v_pk_mul_f32 v[60:61], v[60:61], v[14:15]
	v_pk_mul_f32 v[56:57], v[56:57], v[10:11]
	v_pk_mul_f32 v[52:53], v[52:53], v[6:7]
	v_pk_mul_f32 v[50:51], v[50:51], v[4:5]
	v_pk_mul_f32 v[78:79], v[78:79], v[146:147]
	v_pk_mul_f32 v[74:75], v[74:75], v[12:13]
	v_pk_mul_f32 v[70:71], v[70:71], v[8:9]
	v_pk_mul_f32 v[80:81], v[80:81], v[148:149]
	v_pk_mul_f32 v[76:77], v[76:77], v[14:15]
	v_pk_mul_f32 v[72:73], v[72:73], v[10:11]
	v_pk_mul_f32 v[68:69], v[68:69], v[6:7]
	v_pk_mul_f32 v[66:67], v[66:67], v[4:5]
	v_pk_mul_f32 v[30:31], v[30:31], v[146:147]
	v_pk_mul_f32 v[26:27], v[26:27], v[12:13]
	v_pk_mul_f32 v[22:23], v[22:23], v[8:9]
	v_pk_mul_f32 v[32:33], v[32:33], v[148:149]
	v_pk_mul_f32 v[28:29], v[28:29], v[14:15]
	v_pk_mul_f32 v[24:25], v[24:25], v[10:11]
	v_pk_mul_f32 v[20:21], v[20:21], v[6:7]
	v_pk_mul_f32 v[18:19], v[18:19], v[4:5]
	v_pk_mul_f32 v[46:47], v[46:47], v[146:147]
	v_pk_mul_f32 v[42:43], v[42:43], v[12:13]
	v_pk_mul_f32 v[38:39], v[38:39], v[8:9]
	v_pk_mul_f32 v[48:49], v[48:49], v[148:149]
	v_pk_mul_f32 v[44:45], v[44:45], v[14:15]
	v_pk_mul_f32 v[40:41], v[40:41], v[10:11]
	v_pk_mul_f32 v[36:37], v[36:37], v[6:7]
	v_pk_mul_f32 v[34:35], v[34:35], v[4:5]
	s_branch .LBB0_1385
.Lrotv_exit_1:
	s_waitcnt vmcnt(0)
	s_waitcnt lgkmcnt(0)
	s_barrier
.LBB0_1388:
	ds_read_b128 v[146:149], v2
	ds_read_b128 v[12:15], v2 offset:1024
	ds_read_b128 v[8:11], v2 offset:2048
	ds_read_b128 v[4:7], v2 offset:3072
	s_waitcnt lgkmcnt(0)
	ds_read_b64_tr_b16 v[150:151], v187 offset:0
	ds_read_b64_tr_b16 v[152:153], v187 offset:0x800
	ds_read_b64_tr_b16 v[214:215], v187 offset:0x1000
	ds_read_b64_tr_b16 v[216:217], v187 offset:0x1800
	ds_read_b64_tr_b16 v[218:219], v187 offset:0x2000
	s_lshl_b64 s[0:1], s[0:1], 1
	v_readlane_b32 s6, v250, 42
	ds_read_b64_tr_b16 v[220:221], v187 offset:0x2800
	s_add_u32 s0, s6, s0
	v_readlane_b32 s6, v250, 43
	ds_read_b64_tr_b16 v[222:223], v187 offset:0x3000
	s_addc_u32 s1, s6, s1
	s_lshl_b32 s6, s58, 1
	ds_read_b64_tr_b16 v[224:225], v187 offset:0x3800
	s_add_u32 s0, s0, s6
	s_addc_u32 s1, s1, 0
	ds_read_b64_tr_b16 v[226:227], v187 offset:0x200
	ds_read_b64_tr_b16 v[228:229], v187 offset:0xa00
	ds_read_b64_tr_b16 v[230:231], v187 offset:0x1200
	ds_read_b64_tr_b16 v[232:233], v187 offset:0x1a00
	ds_read_b64_tr_b16 v[234:235], v187 offset:0x2200
	ds_read_b64_tr_b16 v[236:237], v187 offset:0x2a00
	ds_read_b64_tr_b16 v[238:239], v187 offset:0x3200
	ds_read_b64_tr_b16 v[240:241], v187 offset:0x3a00
	s_waitcnt lgkmcnt(8)
	s_waitcnt lgkmcnt(0)
	v_mfma_f32_32x32x16_bf16 v[114:129], v[146:149], v[150:153], v[114:129]
	v_mfma_f32_32x32x16_bf16 v[114:129], v[12:15], v[214:217], v[114:129]
	v_mfma_f32_32x32x16_bf16 v[114:129], v[8:11], v[218:221], v[114:129]
	v_mfma_f32_32x32x16_bf16 v[114:129], v[4:7], v[222:225], v[114:129]
	ds_read_b64_tr_b16 v[150:151], v187 offset:0x400
	ds_read_b64_tr_b16 v[152:153], v187 offset:0xc00
	ds_read_b64_tr_b16 v[214:215], v187 offset:0x1400
	ds_read_b64_tr_b16 v[216:217], v187 offset:0x1c00
	ds_read_b64_tr_b16 v[218:219], v187 offset:0x2400
	ds_read_b64_tr_b16 v[220:221], v187 offset:0x2c00
	ds_read_b64_tr_b16 v[222:223], v187 offset:0x3400
	ds_read_b64_tr_b16 v[224:225], v187 offset:0x3c00
	s_waitcnt lgkmcnt(8)
	v_mfma_f32_32x32x16_bf16 v[130:145], v[146:149], v[226:229], v[130:145]
	v_mfma_f32_32x32x16_bf16 v[130:145], v[12:15], v[230:233], v[130:145]
	v_mfma_f32_32x32x16_bf16 v[130:145], v[8:11], v[234:237], v[130:145]
	v_mfma_f32_32x32x16_bf16 v[130:145], v[4:7], v[238:241], v[130:145]
	ds_read_b64_tr_b16 v[226:227], v187 offset:0x600
	ds_read_b64_tr_b16 v[228:229], v187 offset:0xe00
	ds_read_b64_tr_b16 v[230:231], v187 offset:0x1600
	ds_read_b64_tr_b16 v[232:233], v187 offset:0x1e00
	ds_read_b64_tr_b16 v[234:235], v187 offset:0x2600
	ds_read_b64_tr_b16 v[236:237], v187 offset:0x2e00
	ds_read_b64_tr_b16 v[238:239], v187 offset:0x3600
	ds_read_b64_tr_b16 v[240:241], v187 offset:0x3e00
	s_waitcnt lgkmcnt(8)
	v_mfma_f32_32x32x16_bf16 v[82:97], v[146:149], v[150:153], v[82:97]
	v_mfma_f32_32x32x16_bf16 v[82:97], v[12:15], v[214:217], v[82:97]
	v_mfma_f32_32x32x16_bf16 v[82:97], v[8:11], v[218:221], v[82:97]
	v_mfma_f32_32x32x16_bf16 v[82:97], v[4:7], v[222:225], v[82:97]
	s_waitcnt lgkmcnt(0)
	v_mfma_f32_32x32x16_bf16 v[98:113], v[146:149], v[226:229], v[98:113]
	ds_read_b64_tr_b16 v[150:151], v188 offset:0
	ds_read_b64_tr_b16 v[152:153], v188 offset:0x800
	ds_read_b64_tr_b16 v[214:215], v188 offset:0x1000
	ds_read_b64_tr_b16 v[216:217], v188 offset:0x1800
	ds_read_b64_tr_b16 v[218:219], v188 offset:0x2000
	ds_read_b64_tr_b16 v[220:221], v188 offset:0x2800
	ds_read_b64_tr_b16 v[222:223], v188 offset:0x3000
	v_mfma_f32_32x32x16_bf16 v[98:113], v[12:15], v[230:233], v[98:113]
	ds_read_b64_tr_b16 v[224:225], v188 offset:0x3800
	v_mfma_f32_32x32x16_bf16 v[98:113], v[8:11], v[234:237], v[98:113]
	v_mfma_f32_32x32x16_bf16 v[98:113], v[4:7], v[238:241], v[98:113]
	ds_read_b64_tr_b16 v[226:227], v188 offset:0x200
	ds_read_b64_tr_b16 v[228:229], v188 offset:0xa00
	ds_read_b64_tr_b16 v[230:231], v188 offset:0x1200
	ds_read_b64_tr_b16 v[232:233], v188 offset:0x1a00
	ds_read_b64_tr_b16 v[234:235], v188 offset:0x2200
	ds_read_b64_tr_b16 v[236:237], v188 offset:0x2a00
	ds_read_b64_tr_b16 v[238:239], v188 offset:0x3200
	ds_read_b64_tr_b16 v[240:241], v188 offset:0x3a00
	s_waitcnt lgkmcnt(8)
	v_mfma_f32_32x32x16_bf16 v[50:65], v[146:149], v[150:153], v[50:65]
	v_mfma_f32_32x32x16_bf16 v[50:65], v[12:15], v[214:217], v[50:65]
	v_mfma_f32_32x32x16_bf16 v[50:65], v[8:11], v[218:221], v[50:65]
	v_mfma_f32_32x32x16_bf16 v[50:65], v[4:7], v[222:225], v[50:65]
	ds_read_b64_tr_b16 v[214:215], v188 offset:0x400
	ds_read_b64_tr_b16 v[216:217], v188 offset:0xc00
	ds_read_b64_tr_b16 v[218:219], v188 offset:0x1400
	ds_read_b64_tr_b16 v[220:221], v188 offset:0x1c00
	ds_read_b64_tr_b16 v[222:223], v188 offset:0x2400
	ds_read_b64_tr_b16 v[224:225], v188 offset:0x2c00
	ds_read_b64_tr_b16 v[242:243], v188 offset:0x3400
	ds_read_b64_tr_b16 v[244:245], v188 offset:0x3c00
	s_waitcnt lgkmcnt(8)
	v_mfma_f32_32x32x16_bf16 v[66:81], v[146:149], v[226:229], v[66:81]
	v_mfma_f32_32x32x16_bf16 v[66:81], v[12:15], v[230:233], v[66:81]
	v_mfma_f32_32x32x16_bf16 v[66:81], v[8:11], v[234:237], v[66:81]
	v_mfma_f32_32x32x16_bf16 v[66:81], v[4:7], v[238:241], v[66:81]
	ds_read_b64_tr_b16 v[226:227], v188 offset:0x600
	ds_read_b64_tr_b16 v[228:229], v188 offset:0xe00
	ds_read_b64_tr_b16 v[230:231], v188 offset:0x1600
	ds_read_b64_tr_b16 v[232:233], v188 offset:0x1e00
	ds_read_b64_tr_b16 v[234:235], v188 offset:0x2600
	ds_read_b64_tr_b16 v[236:237], v188 offset:0x2e00
	ds_read_b64_tr_b16 v[150:151], v188 offset:0x3600
	ds_read_b64_tr_b16 v[152:153], v188 offset:0x3e00
	s_waitcnt lgkmcnt(8)
	v_mfma_f32_32x32x16_bf16 v[18:33], v[146:149], v[214:217], v[18:33]
	v_mfma_f32_32x32x16_bf16 v[18:33], v[12:15], v[218:221], v[18:33]
	v_mfma_f32_32x32x16_bf16 v[18:33], v[8:11], v[222:225], v[18:33]
	v_mfma_f32_32x32x16_bf16 v[18:33], v[4:7], v[242:245], v[18:33]
	s_waitcnt lgkmcnt(0)
	v_add_u32_e32 v2, s20, v163
	ds_read_b128 v[214:217], v2 offset:128
	ds_read_b128 v[238:241], v2 offset:160
	v_mfma_f32_32x32x16_bf16 v[34:49], v[146:149], v[226:229], v[34:49]
	ds_read_b128 v[146:149], v2 offset:192
	ds_read_b128 v[224:227], v2 offset:224
	s_waitcnt lgkmcnt(0)
	v_rcp_f32_e32 v223, v214
	v_rcp_f32_e32 v222, v215
	v_lshlrev_b32_e32 v2, 1, v1
	v_rcp_f32_e32 v177, v149
	s_waitcnt vmcnt(0)
	v_mfma_f32_32x32x16_bf16 v[34:49], v[12:15], v[230:233], v[34:49]
	v_mul_f32_e32 v12, v114, v223
	v_add3_u32 v149, s18, v165, v2
	v_cvt_pk_bf16_f32 v12, v12, v12
	v_rcp_f32_e32 v221, v216
	v_mul_f32_e32 v13, v130, v223
	ds_write_b16 v149, v12
	v_cvt_pk_bf16_f32 v12, v13, v13
	ds_write_b16 v149, v12 offset:64
	v_mul_f32_e32 v12, v115, v222
	v_cvt_pk_bf16_f32 v12, v12, v12
	v_rcp_f32_e32 v220, v217
	v_mul_f32_e32 v13, v131, v222
	ds_write_b16 v149, v12 offset:128
	v_cvt_pk_bf16_f32 v12, v13, v13
	ds_write_b16 v149, v12 offset:192
	v_mul_f32_e32 v12, v116, v221
	v_cvt_pk_bf16_f32 v12, v12, v12
	v_rcp_f32_e32 v219, v238
	v_mul_f32_e32 v13, v132, v221
	ds_write_b16 v149, v12 offset:256
	v_cvt_pk_bf16_f32 v12, v13, v13
	ds_write_b16 v149, v12 offset:320
	v_mul_f32_e32 v12, v117, v220
	v_cvt_pk_bf16_f32 v12, v12, v12
	v_rcp_f32_e32 v218, v239
	v_mul_f32_e32 v13, v133, v220
	ds_write_b16 v149, v12 offset:384
	v_cvt_pk_bf16_f32 v12, v13, v13
	ds_write_b16 v149, v12 offset:448
	v_mul_f32_e32 v12, v118, v219
	v_cvt_pk_bf16_f32 v12, v12, v12
	v_rcp_f32_e32 v217, v240
	v_mul_f32_e32 v13, v134, v219
	ds_write_b16 v149, v12 offset:1024
	v_cvt_pk_bf16_f32 v12, v13, v13
	ds_write_b16 v149, v12 offset:1088
	v_mul_f32_e32 v12, v119, v218
	v_cvt_pk_bf16_f32 v12, v12, v12
	v_rcp_f32_e32 v216, v241
	v_mul_f32_e32 v13, v135, v218
	ds_write_b16 v149, v12 offset:1152
	v_cvt_pk_bf16_f32 v12, v13, v13
	ds_write_b16 v149, v12 offset:1216
	v_mul_f32_e32 v12, v120, v217
	v_cvt_pk_bf16_f32 v12, v12, v12
	v_rcp_f32_e32 v215, v146
	v_mul_f32_e32 v13, v136, v217
	ds_write_b16 v149, v12 offset:1280
	v_cvt_pk_bf16_f32 v12, v13, v13
	ds_write_b16 v149, v12 offset:1344
	v_mul_f32_e32 v12, v121, v216
	v_cvt_pk_bf16_f32 v12, v12, v12
	v_rcp_f32_e32 v214, v147
	v_mul_f32_e32 v13, v137, v216
	ds_write_b16 v149, v12 offset:1408
	v_cvt_pk_bf16_f32 v12, v13, v13
	ds_write_b16 v149, v12 offset:1472
	v_mul_f32_e32 v12, v122, v215
	v_cvt_pk_bf16_f32 v12, v12, v12
	v_rcp_f32_e32 v183, v148
	v_mul_f32_e32 v13, v138, v215
	ds_write_b16 v149, v12 offset:2048
	v_cvt_pk_bf16_f32 v12, v13, v13
	ds_write_b16 v149, v12 offset:2112
	v_mul_f32_e32 v12, v123, v214
	v_cvt_pk_bf16_f32 v12, v12, v12
	v_mul_f32_e32 v13, v139, v214
	ds_write_b16 v149, v12 offset:2176
	v_cvt_pk_bf16_f32 v12, v13, v13
	ds_write_b16 v149, v12 offset:2240
	v_mul_f32_e32 v12, v124, v183
	v_cvt_pk_bf16_f32 v12, v12, v12
	v_rcp_f32_e32 v173, v224
	v_mul_f32_e32 v13, v140, v183
	ds_write_b16 v149, v12 offset:2304
	v_cvt_pk_bf16_f32 v12, v13, v13
	ds_write_b16 v149, v12 offset:2368
	v_mul_f32_e32 v12, v125, v177
	v_cvt_pk_bf16_f32 v12, v12, v12
	v_rcp_f32_e32 v157, v225
	v_mul_f32_e32 v13, v141, v177
	ds_write_b16 v149, v12 offset:2432
	v_cvt_pk_bf16_f32 v12, v13, v13
	ds_write_b16 v149, v12 offset:2496
	v_mul_f32_e32 v12, v126, v173
	v_cvt_pk_bf16_f32 v12, v12, v12
	v_rcp_f32_e32 v155, v226
	v_mul_f32_e32 v13, v142, v173
	ds_write_b16 v149, v12 offset:3072
	v_cvt_pk_bf16_f32 v12, v13, v13
	ds_write_b16 v149, v12 offset:3136
	v_mul_f32_e32 v12, v127, v157
	v_cvt_pk_bf16_f32 v12, v12, v12
	v_rcp_f32_e32 v148, v227
	v_mul_f32_e32 v13, v143, v157
	ds_write_b16 v149, v12 offset:3200
	v_cvt_pk_bf16_f32 v12, v13, v13
	ds_write_b16 v149, v12 offset:3264
	v_mul_f32_e32 v12, v128, v155
	v_cvt_pk_bf16_f32 v12, v12, v12
	v_mul_f32_e32 v13, v144, v155
	ds_write_b16 v149, v12 offset:3328
	v_cvt_pk_bf16_f32 v12, v13, v13
	s_lshl_b32 s6, s59, 18
	ds_write_b16 v149, v12 offset:3392
	v_mul_f32_e32 v12, v129, v148
	s_add_u32 s6, s53, s6
	v_cvt_pk_bf16_f32 v12, v12, v12
	s_addc_u32 s7, s54, 0
	v_lshlrev_b32_e32 v2, 1, v160
	v_mul_f32_e32 v13, v145, v148
	ds_write_b16 v149, v12 offset:3456
	v_cvt_pk_bf16_f32 v12, v13, v13
	v_lshl_add_u64 v[146:147], s[6:7], 0, v[2:3]
	ds_write_b16 v149, v12 offset:3520
	v_lshlrev_b32_e32 v12, 1, v162
	v_mov_b32_e32 v13, v3
	s_waitcnt lgkmcnt(0)
	v_lshl_add_u64 v[128:129], v[146:147], 0, v[12:13]
	global_load_dwordx4 v[12:15], v[128:129], off
	v_mfma_f32_32x32x16_bf16 v[34:49], v[8:11], v[234:237], v[34:49]
	v_lshlrev_b32_e32 v8, 1, v166
	v_mov_b32_e32 v9, v3
	v_lshl_add_u64 v[124:125], v[146:147], 0, v[8:9]
	global_load_dwordx4 v[8:11], v[124:125], off
	v_add_u32_e32 v118, s18, v2
	v_add_u32_e32 v175, v118, v167
	ds_read_b128 v[114:117], v175
	v_mfma_f32_32x32x16_bf16 v[34:49], v[4:7], v[150:153], v[34:49]
	v_add_u32_e32 v144, v118, v171
	v_add_u32_e32 v150, v118, v181
	v_add_u32_e32 v145, v118, v179
	s_waitcnt lgkmcnt(0)
	v_lshlrev_b32_e32 v5, 16, v114
	v_lshlrev_b32_e32 v6, 16, v115
	v_mul_f32_e32 v50, v50, v223
	v_mul_f32_e32 v66, v66, v223
	s_lshl_b32 s6, s59, 17
	s_add_u32 s0, s0, s6
	s_addc_u32 s1, s1, 0
	s_waitcnt vmcnt(0)
	v_lshlrev_b32_e32 v4, 16, v12
	v_fma_f32 v130, -v158, v5, v4
	v_and_b32_e32 v4, 0xffff0000, v12
	v_and_b32_e32 v5, 0xffff0000, v114
	v_fma_f32 v131, -v158, v5, v4
	v_lshlrev_b32_e32 v5, 16, v13
	v_fma_f32 v132, -v158, v6, v5
	v_and_b32_e32 v5, 0xffff0000, v13
	v_and_b32_e32 v6, 0xffff0000, v115
	v_fma_f32 v133, -v158, v6, v5
	v_mul_f32_e32 v4, v131, v131
	v_mul_f32_e32 v5, v133, v133
	v_fmac_f32_e32 v4, v130, v130
	v_fmac_f32_e32 v5, v132, v132
	v_add_f32_e32 v4, v5, v4
	v_lshlrev_b32_e32 v5, 16, v14
	v_lshlrev_b32_e32 v6, 16, v116
	v_fma_f32 v134, -v158, v6, v5
	v_and_b32_e32 v5, 0xffff0000, v14
	v_and_b32_e32 v6, 0xffff0000, v116
	v_fma_f32 v135, -v158, v6, v5
	v_mul_f32_e32 v5, v135, v135
	v_fmac_f32_e32 v5, v134, v134
	v_add_f32_e32 v4, v5, v4
	v_lshlrev_b32_e32 v5, 16, v15
	v_lshlrev_b32_e32 v6, 16, v117
	v_fma_f32 v136, -v158, v6, v5
	v_and_b32_e32 v5, 0xffff0000, v15
	ds_read_b128 v[14:17], v144
	v_and_b32_e32 v6, 0xffff0000, v117
	v_fma_f32 v138, -v158, v6, v5
	v_mul_f32_e32 v5, v138, v138
	v_fmac_f32_e32 v5, v136, v136
	v_add_f32_e32 v151, v5, v4
	v_lshlrev_b32_e32 v4, 16, v8
	ds_read_b128 v[114:117], v150
	s_waitcnt lgkmcnt(1)
	v_lshlrev_b32_e32 v5, 16, v14
	v_fma_f32 v137, -v158, v5, v4
	v_and_b32_e32 v4, 0xffff0000, v8
	v_and_b32_e32 v5, 0xffff0000, v14
	v_fma_f32 v139, -v158, v5, v4
	v_lshlrev_b32_e32 v5, 16, v9
	v_lshlrev_b32_e32 v6, 16, v15
	v_fma_f32 v140, -v158, v6, v5
	v_and_b32_e32 v5, 0xffff0000, v9
	v_lshlrev_b32_e32 v8, 1, v168
	v_mov_b32_e32 v9, v3
	v_lshl_add_u64 v[126:127], v[146:147], 0, v[8:9]
	v_and_b32_e32 v6, 0xffff0000, v15
	global_load_dwordx4 v[12:15], v[126:127], off
	v_fma_f32 v141, -v158, v6, v5
	v_mul_f32_e32 v4, v139, v139
	v_mul_f32_e32 v5, v141, v141
	v_fmac_f32_e32 v4, v137, v137
	v_fmac_f32_e32 v5, v140, v140
	v_add_f32_e32 v4, v5, v4
	v_lshlrev_b32_e32 v5, 16, v10
	v_lshlrev_b32_e32 v6, 16, v16
	v_fma_f32 v142, -v158, v6, v5
	v_and_b32_e32 v5, 0xffff0000, v10
	v_and_b32_e32 v6, 0xffff0000, v16
	v_fma_f32 v143, -v158, v6, v5
	v_mul_f32_e32 v5, v143, v143
	v_lshlrev_b32_e32 v8, 1, v170
	v_fmac_f32_e32 v5, v142, v142
	v_lshl_add_u64 v[122:123], v[146:147], 0, v[8:9]
	v_mul_f32_e32 v8, v82, v223
	v_add_f32_e32 v10, v5, v4
	ds_read_b128 v[4:7], v145
	global_load_dwordx4 v[118:121], v[122:123], off
	s_waitcnt lgkmcnt(0)
	v_cvt_pk_bf16_f32 v8, v8, v8
	v_mul_f32_e32 v9, v98, v223
	ds_write_b16 v149, v8
	v_cvt_pk_bf16_f32 v8, v9, v9
	ds_write_b16 v149, v8 offset:64
	v_mul_f32_e32 v8, v83, v222
	v_cvt_pk_bf16_f32 v8, v8, v8
	v_mul_f32_e32 v9, v99, v222
	ds_write_b16 v149, v8 offset:128
	v_cvt_pk_bf16_f32 v8, v9, v9
	ds_write_b16 v149, v8 offset:192
	v_mul_f32_e32 v8, v84, v221
	v_cvt_pk_bf16_f32 v8, v8, v8
	v_mul_f32_e32 v9, v100, v221
	ds_write_b16 v149, v8 offset:256
	v_cvt_pk_bf16_f32 v8, v9, v9
	ds_write_b16 v149, v8 offset:320
	v_mul_f32_e32 v8, v85, v220
	v_cvt_pk_bf16_f32 v8, v8, v8
	v_mul_f32_e32 v9, v101, v220
	ds_write_b16 v149, v8 offset:384
	v_cvt_pk_bf16_f32 v8, v9, v9
	ds_write_b16 v149, v8 offset:448
	v_mul_f32_e32 v8, v86, v219
	v_cvt_pk_bf16_f32 v8, v8, v8
	v_mul_f32_e32 v9, v102, v219
	ds_write_b16 v149, v8 offset:1024
	v_cvt_pk_bf16_f32 v8, v9, v9
	ds_write_b16 v149, v8 offset:1088
	v_mul_f32_e32 v8, v87, v218
	v_cvt_pk_bf16_f32 v8, v8, v8
	v_mul_f32_e32 v9, v103, v218
	ds_write_b16 v149, v8 offset:1152
	v_cvt_pk_bf16_f32 v8, v9, v9
	ds_write_b16 v149, v8 offset:1216
	v_mul_f32_e32 v8, v88, v217
	v_cvt_pk_bf16_f32 v8, v8, v8
	v_mul_f32_e32 v9, v104, v217
	ds_write_b16 v149, v8 offset:1280
	v_cvt_pk_bf16_f32 v8, v9, v9
	ds_write_b16 v149, v8 offset:1344
	v_mul_f32_e32 v8, v89, v216
	v_cvt_pk_bf16_f32 v8, v8, v8
	v_mul_f32_e32 v9, v105, v216
	ds_write_b16 v149, v8 offset:1408
	v_cvt_pk_bf16_f32 v8, v9, v9
	ds_write_b16 v149, v8 offset:1472
	v_mul_f32_e32 v8, v90, v215
	v_cvt_pk_bf16_f32 v8, v8, v8
	v_mul_f32_e32 v9, v106, v215
	ds_write_b16 v149, v8 offset:2048
	v_cvt_pk_bf16_f32 v8, v9, v9
	ds_write_b16 v149, v8 offset:2112
	v_mul_f32_e32 v8, v91, v214
	v_cvt_pk_bf16_f32 v8, v8, v8
	v_mul_f32_e32 v9, v107, v214
	ds_write_b16 v149, v8 offset:2176
	v_cvt_pk_bf16_f32 v8, v9, v9
	ds_write_b16 v149, v8 offset:2240
	v_mul_f32_e32 v8, v92, v183
	v_cvt_pk_bf16_f32 v8, v8, v8
	v_mul_f32_e32 v9, v108, v183
	ds_write_b16 v149, v8 offset:2304
	v_cvt_pk_bf16_f32 v8, v9, v9
	ds_write_b16 v149, v8 offset:2368
	v_mul_f32_e32 v8, v93, v177
	v_cvt_pk_bf16_f32 v8, v8, v8
	v_mul_f32_e32 v9, v109, v177
	ds_write_b16 v149, v8 offset:2432
	v_cvt_pk_bf16_f32 v8, v9, v9
	ds_write_b16 v149, v8 offset:2496
	v_mul_f32_e32 v8, v94, v173
	v_cvt_pk_bf16_f32 v8, v8, v8
	v_mul_f32_e32 v9, v110, v173
	ds_write_b16 v149, v8 offset:3072
	v_cvt_pk_bf16_f32 v8, v9, v9
	ds_write_b16 v149, v8 offset:3136
	v_mul_f32_e32 v8, v95, v157
	v_cvt_pk_bf16_f32 v8, v8, v8
	v_mul_f32_e32 v9, v111, v157
	ds_write_b16 v149, v8 offset:3200
	v_cvt_pk_bf16_f32 v8, v9, v9
	ds_write_b16 v149, v8 offset:3264
	v_mul_f32_e32 v8, v96, v155
	v_cvt_pk_bf16_f32 v8, v8, v8
	v_mul_f32_e32 v9, v112, v155
	ds_write_b16 v149, v8 offset:3328
	v_cvt_pk_bf16_f32 v8, v9, v9
	ds_write_b16 v149, v8 offset:3392
	v_mul_f32_e32 v8, v97, v148
	v_cvt_pk_bf16_f32 v8, v8, v8
	v_mul_f32_e32 v9, v113, v148
	ds_write_b16 v149, v8 offset:3456
	v_cvt_pk_bf16_f32 v8, v9, v9
	ds_write_b16 v149, v8 offset:3520
	s_waitcnt lgkmcnt(0)
	global_load_dwordx4 v[104:107], v[128:129], off offset:128
	v_and_b32_e32 v8, 0xffff0000, v11
	v_and_b32_e32 v9, 0xffff0000, v17
	v_lshlrev_b32_e32 v16, 16, v11
	v_lshlrev_b32_e32 v152, 16, v17
	v_fma_f32 v85, -v158, v9, v8
	v_fma_f32 v83, -v158, v152, v16
	v_mul_f32_e32 v8, v85, v85
	v_fmac_f32_e32 v8, v83, v83
	v_add_f32_e32 v110, v8, v10
	s_waitcnt vmcnt(2)
	v_lshlrev_b32_e32 v8, 16, v12
	s_waitcnt lgkmcnt(14)
	v_lshlrev_b32_e32 v9, 16, v4
	v_fma_f32 v82, -v158, v9, v8
	v_and_b32_e32 v8, 0xffff0000, v12
	v_and_b32_e32 v4, 0xffff0000, v4
	v_fma_f32 v84, -v158, v4, v8
	v_lshlrev_b32_e32 v8, 16, v13
	v_lshlrev_b32_e32 v9, 16, v5
	v_fma_f32 v86, -v158, v9, v8
	v_and_b32_e32 v8, 0xffff0000, v13
	v_and_b32_e32 v5, 0xffff0000, v5
	v_fma_f32 v87, -v158, v5, v8
	v_mul_f32_e32 v4, v84, v84
	v_mul_f32_e32 v5, v87, v87
	v_fmac_f32_e32 v4, v82, v82
	v_fmac_f32_e32 v5, v86, v86
	v_add_f32_e32 v4, v5, v4
	v_lshlrev_b32_e32 v5, 16, v14
	v_lshlrev_b32_e32 v8, 16, v6
	v_fma_f32 v88, -v158, v8, v5
	global_load_dwordx4 v[8:11], v[124:125], off offset:128
	v_and_b32_e32 v5, 0xffff0000, v14
	v_and_b32_e32 v6, 0xffff0000, v6
	v_fma_f32 v89, -v158, v6, v5
	v_mul_f32_e32 v5, v89, v89
	v_fmac_f32_e32 v5, v88, v88
	v_add_f32_e32 v4, v5, v4
	v_lshlrev_b32_e32 v5, 16, v15
	v_lshlrev_b32_e32 v6, 16, v7
	v_fma_f32 v90, -v158, v6, v5
	v_and_b32_e32 v5, 0xffff0000, v15
	v_and_b32_e32 v6, 0xffff0000, v7
	v_fma_f32 v93, -v158, v6, v5
	v_mul_f32_e32 v5, v93, v93
	v_fmac_f32_e32 v5, v90, v90
	v_add_f32_e32 v146, v5, v4
	s_waitcnt vmcnt(2)
	v_lshlrev_b32_e32 v4, 16, v118
	v_lshlrev_b32_e32 v5, 16, v114
	v_fma_f32 v91, -v158, v5, v4
	v_and_b32_e32 v4, 0xffff0000, v118
	v_and_b32_e32 v5, 0xffff0000, v114
	v_fma_f32 v92, -v158, v5, v4
	v_lshlrev_b32_e32 v5, 16, v119
	v_lshlrev_b32_e32 v6, 16, v115
	v_fma_f32 v94, -v158, v6, v5
	v_and_b32_e32 v5, 0xffff0000, v119
	v_and_b32_e32 v6, 0xffff0000, v115
	v_fma_f32 v95, -v158, v6, v5
	v_mul_f32_e32 v4, v92, v92
	v_mul_f32_e32 v5, v95, v95
	v_fmac_f32_e32 v4, v91, v91
	v_fmac_f32_e32 v5, v94, v94
	v_add_f32_e32 v4, v5, v4
	v_lshlrev_b32_e32 v5, 16, v120
	v_lshlrev_b32_e32 v6, 16, v116
	v_fma_f32 v96, -v158, v6, v5
	v_and_b32_e32 v5, 0xffff0000, v120
	v_and_b32_e32 v6, 0xffff0000, v116
	v_fma_f32 v97, -v158, v6, v5
	v_mul_f32_e32 v5, v97, v97
	v_fmac_f32_e32 v5, v96, v96
	v_add_f32_e32 v12, v5, v4
	v_lshlrev_b32_e32 v4, 16, v121
	v_lshlrev_b32_e32 v5, 16, v117
	v_fma_f32 v99, -v158, v5, v4
	v_and_b32_e32 v4, 0xffff0000, v121
	v_and_b32_e32 v5, 0xffff0000, v117
	v_fma_f32 v101, -v158, v5, v4
	ds_read_b128 v[4:7], v175
	ds_read_b128 v[14:17], v144
	v_mul_f32_e32 v13, v101, v101
	v_fmac_f32_e32 v13, v99, v99
	v_add_f32_e32 v115, v13, v12
	s_waitcnt vmcnt(1)
	v_lshlrev_b32_e32 v12, 16, v104
	s_waitcnt lgkmcnt(1)
	v_lshlrev_b32_e32 v13, 16, v4
	v_fma_f32 v98, -v158, v13, v12
	v_and_b32_e32 v12, 0xffff0000, v104
	v_and_b32_e32 v4, 0xffff0000, v4
	v_fma_f32 v100, -v158, v4, v12
	v_lshlrev_b32_e32 v12, 16, v105
	v_lshlrev_b32_e32 v13, 16, v5
	v_fma_f32 v102, -v158, v13, v12
	v_and_b32_e32 v12, 0xffff0000, v105
	v_and_b32_e32 v5, 0xffff0000, v5
	v_mul_f32_e32 v4, v100, v100
	v_fma_f32 v103, -v158, v5, v12
	v_fmac_f32_e32 v4, v98, v98
	v_mul_f32_e32 v5, v103, v103
	v_add_f32_e32 v4, v151, v4
	v_fmac_f32_e32 v5, v102, v102
	v_add_f32_e32 v4, v5, v4
	v_lshlrev_b32_e32 v5, 16, v106
	v_lshlrev_b32_e32 v12, 16, v6
	v_fma_f32 v104, -v158, v12, v5
	v_and_b32_e32 v5, 0xffff0000, v106
	v_and_b32_e32 v6, 0xffff0000, v6
	v_fma_f32 v105, -v158, v6, v5
	v_mul_f32_e32 v5, v105, v105
	v_fmac_f32_e32 v5, v104, v104
	v_add_f32_e32 v4, v5, v4
	v_lshlrev_b32_e32 v5, 16, v107
	v_lshlrev_b32_e32 v6, 16, v7
	v_fma_f32 v106, -v158, v6, v5
	v_and_b32_e32 v5, 0xffff0000, v107
	v_and_b32_e32 v6, 0xffff0000, v7
	v_fma_f32 v107, -v158, v6, v5
	v_mul_f32_e32 v5, v107, v107
	global_load_dwordx4 v[116:119], v[126:127], off offset:128
	v_fmac_f32_e32 v5, v106, v106
	v_add_f32_e32 v120, v5, v4
	s_waitcnt vmcnt(1)
	v_lshlrev_b32_e32 v4, 16, v8
	s_waitcnt lgkmcnt(0)
	v_lshlrev_b32_e32 v5, 16, v14
	v_fma_f32 v108, -v158, v5, v4
	v_and_b32_e32 v4, 0xffff0000, v8
	v_and_b32_e32 v5, 0xffff0000, v14
	v_fma_f32 v109, -v158, v5, v4
	v_mul_f32_e32 v4, v109, v109
	v_fmac_f32_e32 v4, v108, v108
	v_lshlrev_b32_e32 v5, 16, v9
	v_lshlrev_b32_e32 v6, 16, v15
	v_add_f32_e32 v4, v110, v4
	v_fma_f32 v110, -v158, v6, v5
	v_and_b32_e32 v5, 0xffff0000, v9
	v_and_b32_e32 v6, 0xffff0000, v15
	v_fma_f32 v111, -v158, v6, v5
	v_mul_f32_e32 v5, v111, v111
	v_fmac_f32_e32 v5, v110, v110
	v_add_f32_e32 v4, v5, v4
	v_lshlrev_b32_e32 v5, 16, v10
	v_lshlrev_b32_e32 v6, 16, v16
	v_fma_f32 v112, -v158, v6, v5
	v_and_b32_e32 v5, 0xffff0000, v10
	v_and_b32_e32 v6, 0xffff0000, v16
	v_fma_f32 v113, -v158, v6, v5
	v_mul_f32_e32 v5, v113, v113
	v_fmac_f32_e32 v5, v112, v112
	v_add_f32_e32 v16, v5, v4
	v_lshlrev_b32_e32 v4, 16, v11
	v_lshlrev_b32_e32 v5, 16, v17
	v_fma_f32 v114, -v158, v5, v4
	v_and_b32_e32 v121, 0xffff0000, v11
	ds_read_b128 v[4:7], v145
	ds_read_b128 v[8:11], v150
	global_load_dwordx4 v[12:15], v[122:123], off offset:128
	s_waitcnt lgkmcnt(0)
	v_cvt_pk_bf16_f32 v50, v50, v50
	ds_write_b16 v149, v50
	v_cvt_pk_bf16_f32 v50, v66, v66
	ds_write_b16 v149, v50 offset:64
	v_mul_f32_e32 v50, v51, v222
	v_cvt_pk_bf16_f32 v50, v50, v50
	v_mul_f32_e32 v51, v67, v222
	ds_write_b16 v149, v50 offset:128
	v_cvt_pk_bf16_f32 v50, v51, v51
	ds_write_b16 v149, v50 offset:192
	v_mul_f32_e32 v50, v52, v221
	v_cvt_pk_bf16_f32 v50, v50, v50
	v_mul_f32_e32 v51, v68, v221
	ds_write_b16 v149, v50 offset:256
	v_cvt_pk_bf16_f32 v50, v51, v51
	ds_write_b16 v149, v50 offset:320
	v_mul_f32_e32 v50, v53, v220
	v_cvt_pk_bf16_f32 v50, v50, v50
	v_mul_f32_e32 v51, v69, v220
	ds_write_b16 v149, v50 offset:384
	v_cvt_pk_bf16_f32 v50, v51, v51
	ds_write_b16 v149, v50 offset:448
	v_mul_f32_e32 v50, v54, v219
	v_cvt_pk_bf16_f32 v50, v50, v50
	v_mul_f32_e32 v51, v70, v219
	ds_write_b16 v149, v50 offset:1024
	v_cvt_pk_bf16_f32 v50, v51, v51
	ds_write_b16 v149, v50 offset:1088
	v_mul_f32_e32 v50, v55, v218
	v_cvt_pk_bf16_f32 v50, v50, v50
	v_mul_f32_e32 v51, v71, v218
	ds_write_b16 v149, v50 offset:1152
	v_cvt_pk_bf16_f32 v50, v51, v51
	ds_write_b16 v149, v50 offset:1216
	v_mul_f32_e32 v50, v56, v217
	v_cvt_pk_bf16_f32 v50, v50, v50
	v_mul_f32_e32 v51, v72, v217
	ds_write_b16 v149, v50 offset:1280
	v_cvt_pk_bf16_f32 v50, v51, v51
	ds_write_b16 v149, v50 offset:1344
	v_mul_f32_e32 v50, v57, v216
	v_cvt_pk_bf16_f32 v50, v50, v50
	v_mul_f32_e32 v51, v73, v216
	ds_write_b16 v149, v50 offset:1408
	v_cvt_pk_bf16_f32 v50, v51, v51
	ds_write_b16 v149, v50 offset:1472
	v_mul_f32_e32 v50, v58, v215
	v_cvt_pk_bf16_f32 v50, v50, v50
	v_mul_f32_e32 v51, v74, v215
	ds_write_b16 v149, v50 offset:2048
	v_cvt_pk_bf16_f32 v50, v51, v51
	ds_write_b16 v149, v50 offset:2112
	v_mul_f32_e32 v50, v59, v214
	v_cvt_pk_bf16_f32 v50, v50, v50
	v_mul_f32_e32 v51, v75, v214
	ds_write_b16 v149, v50 offset:2176
	v_cvt_pk_bf16_f32 v50, v51, v51
	ds_write_b16 v149, v50 offset:2240
	v_mul_f32_e32 v50, v60, v183
	v_cvt_pk_bf16_f32 v50, v50, v50
	v_mul_f32_e32 v51, v76, v183
	ds_write_b16 v149, v50 offset:2304
	v_cvt_pk_bf16_f32 v50, v51, v51
	ds_write_b16 v149, v50 offset:2368
	v_mul_f32_e32 v50, v61, v177
	v_cvt_pk_bf16_f32 v50, v50, v50
	v_mul_f32_e32 v51, v77, v177
	ds_write_b16 v149, v50 offset:2432
	v_cvt_pk_bf16_f32 v50, v51, v51
	ds_write_b16 v149, v50 offset:2496
	v_mul_f32_e32 v50, v62, v173
	v_cvt_pk_bf16_f32 v50, v50, v50
	v_mul_f32_e32 v51, v78, v173
	ds_write_b16 v149, v50 offset:3072
	v_cvt_pk_bf16_f32 v50, v51, v51
	ds_write_b16 v149, v50 offset:3136
	v_mul_f32_e32 v50, v63, v157
	v_cvt_pk_bf16_f32 v50, v50, v50
	v_mul_f32_e32 v51, v79, v157
	ds_write_b16 v149, v50 offset:3200
	v_cvt_pk_bf16_f32 v50, v51, v51
	ds_write_b16 v149, v50 offset:3264
	v_mul_f32_e32 v50, v64, v155
	v_cvt_pk_bf16_f32 v50, v50, v50
	v_mul_f32_e32 v51, v80, v155
	ds_write_b16 v149, v50 offset:3328
	v_cvt_pk_bf16_f32 v50, v51, v51
	ds_write_b16 v149, v50 offset:3392
	v_mul_f32_e32 v50, v65, v148
	v_cvt_pk_bf16_f32 v50, v50, v50
	v_mul_f32_e32 v51, v81, v148
	ds_write_b16 v149, v50 offset:3456
	v_cvt_pk_bf16_f32 v50, v51, v51
	ds_write_b16 v149, v50 offset:3520
	s_waitcnt lgkmcnt(0)
	global_load_dwordx4 v[50:53], v[128:129], off offset:256
	v_and_b32_e32 v17, 0xffff0000, v17
	v_fma_f32 v55, -v158, v17, v121
	v_mul_f32_e32 v17, v55, v55
	v_fmac_f32_e32 v17, v114, v114
	v_add_f32_e32 v16, v17, v16
	s_waitcnt vmcnt(2)
	v_lshlrev_b32_e32 v17, 16, v116
	s_waitcnt lgkmcnt(14)
	v_lshlrev_b32_e32 v54, 16, v4
	v_fma_f32 v54, -v158, v54, v17
	v_and_b32_e32 v17, 0xffff0000, v116
	v_and_b32_e32 v4, 0xffff0000, v4
	v_fma_f32 v56, -v158, v4, v17
	v_lshlrev_b32_e32 v17, 16, v117
	v_lshlrev_b32_e32 v57, 16, v5
	v_fma_f32 v57, -v158, v57, v17
	v_and_b32_e32 v17, 0xffff0000, v117
	v_and_b32_e32 v5, 0xffff0000, v5
	v_mul_f32_e32 v4, v56, v56
	v_fma_f32 v58, -v158, v5, v17
	v_fmac_f32_e32 v4, v54, v54
	v_mul_f32_e32 v5, v58, v58
	v_add_f32_e32 v4, v146, v4
	v_fmac_f32_e32 v5, v57, v57
	v_add_f32_e32 v4, v5, v4
	v_lshlrev_b32_e32 v5, 16, v118
	v_lshlrev_b32_e32 v17, 16, v6
	v_fma_f32 v59, -v158, v17, v5
	v_and_b32_e32 v5, 0xffff0000, v118
	v_and_b32_e32 v6, 0xffff0000, v6
	v_fma_f32 v60, -v158, v6, v5
	v_mul_f32_e32 v5, v60, v60
	v_fmac_f32_e32 v5, v59, v59
	v_add_f32_e32 v4, v5, v4
	v_lshlrev_b32_e32 v5, 16, v119
	v_lshlrev_b32_e32 v6, 16, v7
	v_fma_f32 v61, -v158, v6, v5
	v_and_b32_e32 v5, 0xffff0000, v119
	global_load_dwordx4 v[116:119], v[124:125], off offset:256
	v_and_b32_e32 v6, 0xffff0000, v7
	v_fma_f32 v63, -v158, v6, v5
	v_mul_f32_e32 v5, v63, v63
	v_fmac_f32_e32 v5, v61, v61
	v_add_f32_e32 v121, v5, v4
	s_waitcnt vmcnt(2)
	v_lshlrev_b32_e32 v4, 16, v12
	v_lshlrev_b32_e32 v5, 16, v8
	v_fma_f32 v62, -v158, v5, v4
	v_and_b32_e32 v4, 0xffff0000, v12
	v_and_b32_e32 v5, 0xffff0000, v8
	v_fma_f32 v64, -v158, v5, v4
	v_lshlrev_b32_e32 v5, 16, v13
	v_lshlrev_b32_e32 v6, 16, v9
	v_fma_f32 v65, -v158, v6, v5
	v_and_b32_e32 v5, 0xffff0000, v13
	v_and_b32_e32 v6, 0xffff0000, v9
	v_mul_f32_e32 v4, v64, v64
	v_fma_f32 v66, -v158, v6, v5
	v_fmac_f32_e32 v4, v62, v62
	v_mul_f32_e32 v5, v66, v66
	v_add_f32_e32 v4, v115, v4
	v_fmac_f32_e32 v5, v65, v65
	v_add_f32_e32 v4, v5, v4
	v_lshlrev_b32_e32 v5, 16, v14
	v_lshlrev_b32_e32 v6, 16, v10
	v_fma_f32 v67, -v158, v6, v5
	v_and_b32_e32 v5, 0xffff0000, v14
	v_and_b32_e32 v6, 0xffff0000, v10
	v_fma_f32 v68, -v158, v6, v5
	v_mul_f32_e32 v5, v68, v68
	v_fmac_f32_e32 v5, v67, v67
	v_add_f32_e32 v8, v5, v4
	v_lshlrev_b32_e32 v4, 16, v15
	v_lshlrev_b32_e32 v5, 16, v11
	v_fma_f32 v69, -v158, v5, v4
	v_and_b32_e32 v4, 0xffff0000, v15
	v_and_b32_e32 v5, 0xffff0000, v11
	v_fma_f32 v70, -v158, v5, v4
	ds_read_b128 v[4:7], v175
	v_mul_f32_e32 v9, v70, v70
	v_fmac_f32_e32 v9, v69, v69
	v_add_f32_e32 v146, v9, v8
	s_waitcnt vmcnt(1)
	v_lshlrev_b32_e32 v8, 16, v50
	s_waitcnt lgkmcnt(0)
	v_lshlrev_b32_e32 v9, 16, v4
	v_fma_f32 v71, -v158, v9, v8
	v_and_b32_e32 v8, 0xffff0000, v50
	v_and_b32_e32 v4, 0xffff0000, v4
	v_fma_f32 v72, -v158, v4, v8
	v_lshlrev_b32_e32 v8, 16, v51
	v_lshlrev_b32_e32 v9, 16, v5
	v_fma_f32 v73, -v158, v9, v8
	v_and_b32_e32 v8, 0xffff0000, v51
	v_and_b32_e32 v5, 0xffff0000, v5
	v_mul_f32_e32 v4, v72, v72
	v_fma_f32 v74, -v158, v5, v8
	v_fmac_f32_e32 v4, v71, v71
	v_mul_f32_e32 v5, v74, v74
	v_add_f32_e32 v4, v120, v4
	v_fmac_f32_e32 v5, v73, v73
	v_add_f32_e32 v4, v5, v4
	v_lshlrev_b32_e32 v5, 16, v52
	v_lshlrev_b32_e32 v8, 16, v6
	v_fma_f32 v75, -v158, v8, v5
	v_and_b32_e32 v5, 0xffff0000, v52
	v_and_b32_e32 v6, 0xffff0000, v6
	v_fma_f32 v76, -v158, v6, v5
	v_mul_f32_e32 v5, v76, v76
	v_fmac_f32_e32 v5, v75, v75
	v_add_f32_e32 v8, v5, v4
	v_lshlrev_b32_e32 v4, 16, v53
	v_lshlrev_b32_e32 v5, 16, v7
	v_fma_f32 v77, -v158, v5, v4
	v_and_b32_e32 v4, 0xffff0000, v53
	global_load_dwordx4 v[50:53], v[126:127], off offset:256
	v_and_b32_e32 v5, 0xffff0000, v7
	v_fma_f32 v78, -v158, v5, v4
	ds_read_b128 v[4:7], v144
	ds_read_b128 v[12:15], v145
	v_mul_f32_e32 v9, v78, v78
	v_fmac_f32_e32 v9, v77, v77
	v_add_f32_e32 v120, v9, v8
	s_waitcnt vmcnt(1)
	v_lshlrev_b32_e32 v8, 16, v116
	s_waitcnt lgkmcnt(1)
	v_lshlrev_b32_e32 v9, 16, v4
	v_fma_f32 v79, -v158, v9, v8
	v_and_b32_e32 v8, 0xffff0000, v116
	v_and_b32_e32 v4, 0xffff0000, v4
	v_fma_f32 v80, -v158, v4, v8
	v_lshlrev_b32_e32 v8, 16, v117
	v_lshlrev_b32_e32 v9, 16, v5
	v_fma_f32 v81, -v158, v9, v8
	v_and_b32_e32 v8, 0xffff0000, v117
	v_and_b32_e32 v5, 0xffff0000, v5
	v_mul_f32_e32 v4, v80, v80
	v_fma_f32 v115, -v158, v5, v8
	v_fmac_f32_e32 v4, v79, v79
	v_mul_f32_e32 v5, v115, v115
	v_add_f32_e32 v4, v16, v4
	v_fmac_f32_e32 v5, v81, v81
	v_add_f32_e32 v4, v5, v4
	v_lshlrev_b32_e32 v5, 16, v118
	v_lshlrev_b32_e32 v8, 16, v6
	v_fma_f32 v116, -v158, v8, v5
	v_and_b32_e32 v5, 0xffff0000, v118
	v_and_b32_e32 v6, 0xffff0000, v6
	v_fma_f32 v117, -v158, v6, v5
	v_mul_f32_e32 v5, v117, v117
	v_fmac_f32_e32 v5, v116, v116
	v_add_f32_e32 v147, v5, v4
	v_lshlrev_b32_e32 v4, 16, v119
	v_lshlrev_b32_e32 v5, 16, v7
	v_mul_f32_e32 v16, v18, v223
	v_fma_f32 v118, -v158, v5, v4
	v_and_b32_e32 v151, 0xffff0000, v7
	ds_read_b128 v[4:7], v150
	global_load_dwordx4 v[8:11], v[122:123], off offset:256
	s_waitcnt lgkmcnt(0)
	v_cvt_pk_bf16_f32 v16, v16, v16
	v_mul_f32_e32 v17, v34, v223
	ds_write_b16 v149, v16
	v_cvt_pk_bf16_f32 v16, v17, v17
	ds_write_b16 v149, v16 offset:64
	v_mul_f32_e32 v16, v19, v222
	v_cvt_pk_bf16_f32 v16, v16, v16
	v_mul_f32_e32 v17, v35, v222
	ds_write_b16 v149, v16 offset:128
	v_cvt_pk_bf16_f32 v16, v17, v17
	ds_write_b16 v149, v16 offset:192
	v_mul_f32_e32 v16, v20, v221
	v_cvt_pk_bf16_f32 v16, v16, v16
	v_mul_f32_e32 v17, v36, v221
	ds_write_b16 v149, v16 offset:256
	v_cvt_pk_bf16_f32 v16, v17, v17
	ds_write_b16 v149, v16 offset:320
	v_mul_f32_e32 v16, v21, v220
	v_cvt_pk_bf16_f32 v16, v16, v16
	v_mul_f32_e32 v17, v37, v220
	ds_write_b16 v149, v16 offset:384
	v_cvt_pk_bf16_f32 v16, v17, v17
	ds_write_b16 v149, v16 offset:448
	v_mul_f32_e32 v16, v22, v219
	v_cvt_pk_bf16_f32 v16, v16, v16
	v_mul_f32_e32 v17, v38, v219
	ds_write_b16 v149, v16 offset:1024
	v_cvt_pk_bf16_f32 v16, v17, v17
	ds_write_b16 v149, v16 offset:1088
	v_mul_f32_e32 v16, v23, v218
	v_cvt_pk_bf16_f32 v16, v16, v16
	v_mul_f32_e32 v17, v39, v218
	ds_write_b16 v149, v16 offset:1152
	v_cvt_pk_bf16_f32 v16, v17, v17
	ds_write_b16 v149, v16 offset:1216
	v_mul_f32_e32 v16, v24, v217
	v_cvt_pk_bf16_f32 v16, v16, v16
	v_mul_f32_e32 v17, v40, v217
	ds_write_b16 v149, v16 offset:1280
	v_cvt_pk_bf16_f32 v16, v17, v17
	ds_write_b16 v149, v16 offset:1344
	v_mul_f32_e32 v16, v25, v216
	v_cvt_pk_bf16_f32 v16, v16, v16
	v_mul_f32_e32 v17, v41, v216
	ds_write_b16 v149, v16 offset:1408
	v_cvt_pk_bf16_f32 v16, v17, v17
	ds_write_b16 v149, v16 offset:1472
	v_mul_f32_e32 v16, v26, v215
	v_cvt_pk_bf16_f32 v16, v16, v16
	v_mul_f32_e32 v17, v42, v215
	ds_write_b16 v149, v16 offset:2048
	v_cvt_pk_bf16_f32 v16, v17, v17
	ds_write_b16 v149, v16 offset:2112
	v_mul_f32_e32 v16, v27, v214
	v_cvt_pk_bf16_f32 v16, v16, v16
	v_mul_f32_e32 v17, v43, v214
	ds_write_b16 v149, v16 offset:2176
	v_cvt_pk_bf16_f32 v16, v17, v17
	ds_write_b16 v149, v16 offset:2240
	v_mul_f32_e32 v16, v28, v183
	v_cvt_pk_bf16_f32 v16, v16, v16
	v_mul_f32_e32 v17, v44, v183
	ds_write_b16 v149, v16 offset:2304
	v_cvt_pk_bf16_f32 v16, v17, v17
	ds_write_b16 v149, v16 offset:2368
	v_mul_f32_e32 v16, v29, v177
	v_cvt_pk_bf16_f32 v16, v16, v16
	v_mul_f32_e32 v17, v45, v177
	ds_write_b16 v149, v16 offset:2432
	v_cvt_pk_bf16_f32 v16, v17, v17
	ds_write_b16 v149, v16 offset:2496
	v_mul_f32_e32 v16, v30, v173
	v_cvt_pk_bf16_f32 v16, v16, v16
	v_mul_f32_e32 v17, v46, v173
	ds_write_b16 v149, v16 offset:3072
	v_cvt_pk_bf16_f32 v16, v17, v17
	ds_write_b16 v149, v16 offset:3136
	v_mul_f32_e32 v16, v31, v157
	v_cvt_pk_bf16_f32 v16, v16, v16
	v_mul_f32_e32 v17, v47, v157
	ds_write_b16 v149, v16 offset:3200
	v_cvt_pk_bf16_f32 v16, v17, v17
	ds_write_b16 v149, v16 offset:3264
	v_mul_f32_e32 v16, v32, v155
	v_cvt_pk_bf16_f32 v16, v16, v16
	v_mul_f32_e32 v17, v48, v155
	ds_write_b16 v149, v16 offset:3328
	v_cvt_pk_bf16_f32 v16, v17, v17
	ds_write_b16 v149, v16 offset:3392
	v_mul_f32_e32 v16, v33, v148
	v_cvt_pk_bf16_f32 v16, v16, v16
	v_mul_f32_e32 v17, v49, v148
	ds_write_b16 v149, v16 offset:3456
	v_cvt_pk_bf16_f32 v16, v17, v17
	ds_write_b16 v149, v16 offset:3520
	s_waitcnt lgkmcnt(0)
	v_and_b32_e32 v119, 0xffff0000, v119
	global_load_dwordx4 v[16:19], v[128:129], off offset:384
	global_load_dwordx4 v[24:27], v[126:127], off offset:384
	v_fma_f32 v37, -v158, v151, v119
	v_mul_f32_e32 v20, v37, v37
	v_fmac_f32_e32 v20, v118, v118
	v_add_f32_e32 v28, v20, v147
	s_waitcnt vmcnt(3)
	v_lshlrev_b32_e32 v20, 16, v50
	s_waitcnt lgkmcnt(14)
	v_lshlrev_b32_e32 v21, 16, v12
	v_fma_f32 v36, -v158, v21, v20
	v_and_b32_e32 v20, 0xffff0000, v50
	v_and_b32_e32 v12, 0xffff0000, v12
	v_fma_f32 v38, -v158, v12, v20
	v_lshlrev_b32_e32 v20, 16, v51
	v_lshlrev_b32_e32 v21, 16, v13
	v_fma_f32 v39, -v158, v21, v20
	v_and_b32_e32 v20, 0xffff0000, v51
	v_and_b32_e32 v13, 0xffff0000, v13
	v_mul_f32_e32 v12, v38, v38
	v_fma_f32 v40, -v158, v13, v20
	v_fmac_f32_e32 v12, v36, v36
	v_mul_f32_e32 v13, v40, v40
	v_add_f32_e32 v12, v121, v12
	v_fmac_f32_e32 v13, v39, v39
	v_add_f32_e32 v12, v13, v12
	v_lshlrev_b32_e32 v13, 16, v52
	v_lshlrev_b32_e32 v20, 16, v14
	v_fma_f32 v41, -v158, v20, v13
	global_load_dwordx4 v[20:23], v[124:125], off offset:384
	global_load_dwordx4 v[32:35], v[122:123], off offset:384
	v_and_b32_e32 v13, 0xffff0000, v52
	v_and_b32_e32 v14, 0xffff0000, v14
	v_fma_f32 v42, -v158, v14, v13
	v_mul_f32_e32 v13, v42, v42
	v_fmac_f32_e32 v13, v41, v41
	v_add_f32_e32 v12, v13, v12
	v_lshlrev_b32_e32 v13, 16, v53
	v_lshlrev_b32_e32 v14, 16, v15
	v_fma_f32 v43, -v158, v14, v13
	v_and_b32_e32 v13, 0xffff0000, v53
	v_and_b32_e32 v14, 0xffff0000, v15
	v_fma_f32 v45, -v158, v14, v13
	v_mul_f32_e32 v13, v45, v45
	v_fmac_f32_e32 v13, v43, v43
	v_add_f32_e32 v49, v13, v12
	s_waitcnt vmcnt(4)
	v_lshlrev_b32_e32 v12, 16, v8
	v_lshlrev_b32_e32 v13, 16, v4
	v_and_b32_e32 v8, 0xffff0000, v8
	v_and_b32_e32 v4, 0xffff0000, v4
	v_fma_f32 v44, -v158, v13, v12
	v_fma_f32 v46, -v158, v4, v8
	v_lshlrev_b32_e32 v8, 16, v9
	v_lshlrev_b32_e32 v12, 16, v5
	v_fma_f32 v47, -v158, v12, v8
	v_and_b32_e32 v8, 0xffff0000, v9
	v_and_b32_e32 v5, 0xffff0000, v5
	v_mul_f32_e32 v4, v46, v46
	v_fma_f32 v48, -v158, v5, v8
	v_fmac_f32_e32 v4, v44, v44
	v_mul_f32_e32 v5, v48, v48
	v_add_f32_e32 v4, v146, v4
	v_fmac_f32_e32 v5, v47, v47
	v_add_f32_e32 v4, v5, v4
	v_lshlrev_b32_e32 v5, 16, v10
	v_lshlrev_b32_e32 v8, 16, v6
	v_fma_f32 v119, -v158, v8, v5
	v_and_b32_e32 v5, 0xffff0000, v10
	v_and_b32_e32 v6, 0xffff0000, v6
	v_fma_f32 v126, -v158, v6, v5
	v_mul_f32_e32 v5, v126, v126
	v_fmac_f32_e32 v5, v119, v119
	v_add_f32_e32 v4, v5, v4
	v_lshlrev_b32_e32 v5, 16, v11
	v_lshlrev_b32_e32 v6, 16, v7
	v_fma_f32 v127, -v158, v6, v5
	v_and_b32_e32 v5, 0xffff0000, v11
	ds_read_b128 v[8:11], v175
	v_and_b32_e32 v6, 0xffff0000, v7
	v_fma_f32 v128, -v158, v6, v5
	v_mul_f32_e32 v5, v128, v128
	v_fmac_f32_e32 v5, v127, v127
	v_add_f32_e32 v121, v5, v4
	s_waitcnt vmcnt(3)
	v_lshlrev_b32_e32 v5, 16, v17
	v_lshlrev_b32_e32 v4, 16, v16
	s_waitcnt lgkmcnt(0)
	v_lshlrev_b32_e32 v7, 16, v9
	v_lshlrev_b32_e32 v6, 16, v8
	v_pk_fma_f32 v[4:5], v[158:159], v[6:7], v[4:5] neg_lo:[1,0,0] neg_hi:[1,0,0]
	v_and_b32_e32 v7, 0xffff0000, v17
	v_and_b32_e32 v6, 0xffff0000, v16
	v_and_b32_e32 v9, 0xffff0000, v9
	v_and_b32_e32 v8, 0xffff0000, v8
	v_pk_fma_f32 v[6:7], v[158:159], v[8:9], v[6:7] neg_lo:[1,0,0] neg_hi:[1,0,0]
	v_lshlrev_b32_e32 v13, 16, v11
	v_pk_mul_f32 v[8:9], v[6:7], v[6:7]
	v_lshlrev_b32_e32 v12, 16, v10
	v_pk_fma_f32 v[8:9], v[4:5], v[4:5], v[8:9]
	v_and_b32_e32 v11, 0xffff0000, v11
	v_add_f32_e32 v8, v120, v8
	v_add_f32_e32 v14, v9, v8
	v_lshlrev_b32_e32 v9, 16, v19
	v_lshlrev_b32_e32 v8, 16, v18
	v_pk_fma_f32 v[8:9], v[158:159], v[12:13], v[8:9] neg_lo:[1,0,0] neg_hi:[1,0,0]
	v_and_b32_e32 v13, 0xffff0000, v19
	v_and_b32_e32 v12, 0xffff0000, v18
	v_and_b32_e32 v10, 0xffff0000, v10
	ds_read_b128 v[16:19], v144
	v_pk_fma_f32 v[10:11], v[158:159], v[10:11], v[12:13] neg_lo:[1,0,0] neg_hi:[1,0,0]
	v_xor_b32_e32 v124, 4, v213
	v_pk_mul_f32 v[12:13], v[10:11], v[10:11]
	v_mov_b32_e32 v173, v3
	v_pk_fma_f32 v[12:13], v[8:9], v[8:9], v[12:13]
	s_waitcnt lgkmcnt(0)
	v_lshlrev_b32_e32 v15, 16, v17
	v_add_f32_e32 v12, v12, v14
	v_add_f32_e32 v120, v13, v12
	s_waitcnt vmcnt(1)
	v_lshlrev_b32_e32 v13, 16, v21
	v_lshlrev_b32_e32 v12, 16, v20
	v_lshlrev_b32_e32 v14, 16, v16
	v_pk_fma_f32 v[12:13], v[158:159], v[14:15], v[12:13] neg_lo:[1,0,0] neg_hi:[1,0,0]
	v_and_b32_e32 v15, 0xffff0000, v21
	v_and_b32_e32 v14, 0xffff0000, v20
	v_and_b32_e32 v17, 0xffff0000, v17
	v_and_b32_e32 v16, 0xffff0000, v16
	v_pk_fma_f32 v[14:15], v[158:159], v[16:17], v[14:15] neg_lo:[1,0,0] neg_hi:[1,0,0]
	v_lshlrev_b32_e32 v21, 16, v19
	v_pk_mul_f32 v[16:17], v[14:15], v[14:15]
	v_lshlrev_b32_e32 v20, 16, v18
	v_pk_fma_f32 v[16:17], v[12:13], v[12:13], v[16:17]
	v_and_b32_e32 v19, 0xffff0000, v19
	v_add_f32_e32 v16, v28, v16
	v_add_f32_e32 v50, v17, v16
	v_lshlrev_b32_e32 v17, 16, v23
	v_lshlrev_b32_e32 v16, 16, v22
	v_pk_fma_f32 v[16:17], v[158:159], v[20:21], v[16:17] neg_lo:[1,0,0] neg_hi:[1,0,0]
	v_and_b32_e32 v21, 0xffff0000, v23
	v_and_b32_e32 v20, 0xffff0000, v22
	v_and_b32_e32 v18, 0xffff0000, v18
	ds_read_b128 v[28:31], v145
	v_pk_fma_f32 v[18:19], v[158:159], v[18:19], v[20:21] neg_lo:[1,0,0] neg_hi:[1,0,0]
	v_mov_b32_e32 v175, v3
	v_pk_mul_f32 v[20:21], v[18:19], v[18:19]
	v_mov_b32_e32 v177, v3
	v_pk_fma_f32 v[20:21], v[16:17], v[16:17], v[20:21]
	v_mov_b32_e32 v183, v3
	v_add_f32_e32 v20, v20, v50
	v_add_f32_e32 v122, v21, v20
	v_lshlrev_b32_e32 v21, 16, v25
	v_lshlrev_b32_e32 v20, 16, v24
	ds_read_b128 v[50:53], v150
	s_waitcnt lgkmcnt(1)
	v_lshlrev_b32_e32 v23, 16, v29
	v_lshlrev_b32_e32 v22, 16, v28
	v_pk_fma_f32 v[20:21], v[158:159], v[22:23], v[20:21] neg_lo:[1,0,0] neg_hi:[1,0,0]
	v_and_b32_e32 v23, 0xffff0000, v25
	v_and_b32_e32 v22, 0xffff0000, v24
	v_and_b32_e32 v25, 0xffff0000, v29
	v_and_b32_e32 v24, 0xffff0000, v28
	v_pk_fma_f32 v[22:23], v[158:159], v[24:25], v[22:23] neg_lo:[1,0,0] neg_hi:[1,0,0]
	v_lshlrev_b32_e32 v29, 16, v31
	v_pk_mul_f32 v[24:25], v[22:23], v[22:23]
	v_lshlrev_b32_e32 v28, 16, v30
	v_pk_fma_f32 v[24:25], v[20:21], v[20:21], v[24:25]
	s_waitcnt lgkmcnt(0)
	s_nop 0
	v_add_f32_e32 v24, v49, v24
	v_add_f32_e32 v49, v25, v24
	v_lshlrev_b32_e32 v25, 16, v27
	v_lshlrev_b32_e32 v24, 16, v26
	v_pk_fma_f32 v[24:25], v[158:159], v[28:29], v[24:25] neg_lo:[1,0,0] neg_hi:[1,0,0]
	v_and_b32_e32 v27, 0xffff0000, v27
	v_and_b32_e32 v26, 0xffff0000, v26
	v_and_b32_e32 v29, 0xffff0000, v31
	v_and_b32_e32 v28, 0xffff0000, v30
	v_pk_fma_f32 v[26:27], v[158:159], v[28:29], v[26:27] neg_lo:[1,0,0] neg_hi:[1,0,0]
	s_waitcnt lgkmcnt(0)
	v_lshlrev_b32_e32 v31, 16, v51
	v_pk_mul_f32 v[28:29], v[26:27], v[26:27]
	v_lshlrev_b32_e32 v30, 16, v50
	v_pk_fma_f32 v[28:29], v[24:25], v[24:25], v[28:29]
	s_nop 0
	v_add_f32_e32 v28, v28, v49
	v_add_f32_e32 v49, v29, v28
	s_waitcnt vmcnt(0)
	v_lshlrev_b32_e32 v29, 16, v33
	v_lshlrev_b32_e32 v28, 16, v32
	v_pk_fma_f32 v[28:29], v[158:159], v[30:31], v[28:29] neg_lo:[1,0,0] neg_hi:[1,0,0]
	v_and_b32_e32 v31, 0xffff0000, v33
	v_and_b32_e32 v30, 0xffff0000, v32
	v_and_b32_e32 v33, 0xffff0000, v51
	v_and_b32_e32 v32, 0xffff0000, v50
	v_pk_fma_f32 v[30:31], v[158:159], v[32:33], v[30:31] neg_lo:[1,0,0] neg_hi:[1,0,0]
	v_lshlrev_b32_e32 v51, 16, v53
	v_pk_mul_f32 v[32:33], v[30:31], v[30:31]
	v_lshlrev_b32_e32 v50, 16, v52
	v_pk_fma_f32 v[32:33], v[28:29], v[28:29], v[32:33]
	s_nop 0
	v_add_f32_e32 v32, v121, v32
	v_add_f32_e32 v121, v33, v32
	v_lshlrev_b32_e32 v33, 16, v35
	v_lshlrev_b32_e32 v32, 16, v34
	v_pk_fma_f32 v[32:33], v[158:159], v[50:51], v[32:33] neg_lo:[1,0,0] neg_hi:[1,0,0]
	v_and_b32_e32 v51, 0xffff0000, v53
	v_and_b32_e32 v53, 64, v213
	v_and_b32_e32 v50, 0xffff0000, v52
	v_xor_b32_e32 v52, 1, v213
	v_add_u32_e32 v53, 64, v53
	v_cmp_lt_i32_e32 vcc, v52, v53
	v_and_b32_e32 v35, 0xffff0000, v35
	v_and_b32_e32 v34, 0xffff0000, v34
	v_cndmask_b32_e32 v52, v213, v52, vcc
	v_pk_fma_f32 v[34:35], v[158:159], v[50:51], v[34:35] neg_lo:[1,0,0] neg_hi:[1,0,0]
	v_lshlrev_b32_e32 v52, 2, v52
	v_pk_mul_f32 v[50:51], v[34:35], v[34:35]
	ds_bpermute_b32 v123, v52, v120
	v_pk_fma_f32 v[50:51], v[32:33], v[32:33], v[50:51]
	s_waitcnt lgkmcnt(0)
	v_add_f32_e32 v120, v120, v123
	v_add_f32_e32 v50, v50, v121
	v_xor_b32_e32 v121, 2, v213
	v_cmp_lt_i32_e32 vcc, v121, v53
	v_add_f32_e32 v50, v51, v50
	s_nop 0
	v_cndmask_b32_e32 v121, v213, v121, vcc
	v_lshlrev_b32_e32 v121, 2, v121
	ds_bpermute_b32 v123, v121, v120
	v_cmp_lt_i32_e32 vcc, v124, v53
	s_waitcnt lgkmcnt(0)
	v_add_f32_e32 v120, v120, v123
	v_cndmask_b32_e32 v53, v213, v124, vcc
	v_lshlrev_b32_e32 v53, 2, v53
	ds_bpermute_b32 v123, v53, v120
	ds_bpermute_b32 v124, v52, v122
	s_waitcnt lgkmcnt(1)
	v_add_f32_e32 v120, v120, v123
	ds_bpermute_b32 v123, v52, v49
	ds_bpermute_b32 v52, v52, v50
	s_waitcnt lgkmcnt(2)
	v_add_f32_e32 v51, v122, v124
	ds_bpermute_b32 v122, v121, v51
	v_fmamk_f32 v120, v120, 0x3b800000, v204
	s_waitcnt lgkmcnt(2)
	v_add_f32_e32 v49, v49, v123
	s_waitcnt lgkmcnt(1)
	v_add_f32_e32 v50, v50, v52
	ds_bpermute_b32 v52, v121, v50
	ds_bpermute_b32 v123, v121, v49
	s_waitcnt lgkmcnt(2)
	v_add_f32_e32 v51, v51, v122
	ds_bpermute_b32 v122, v53, v51
	v_rsq_f32_e32 v129, v120
	s_waitcnt lgkmcnt(2)
	v_add_f32_e32 v50, v50, v52
	ds_bpermute_b32 v52, v53, v50
	s_waitcnt lgkmcnt(2)
	v_add_f32_e32 v49, v49, v123
	ds_bpermute_b32 v120, v53, v49
	s_waitcnt lgkmcnt(2)
	v_add_f32_e32 v51, v51, v122
	v_fmamk_f32 v51, v51, 0x3b800000, v204
	s_waitcnt lgkmcnt(1)
	v_add_f32_e32 v50, v50, v52
	v_fmamk_f32 v50, v50, 0x3b800000, v204
	v_rsq_f32_e32 v144, v51
	s_waitcnt lgkmcnt(0)
	v_add_f32_e32 v49, v49, v120
	v_rsq_f32_e32 v145, v50
	v_lshl_add_u64 v[120:121], s[0:1], 0, v[2:3]
	v_mul_f32_e32 v2, v130, v129
	v_mul_f32_e32 v50, v131, v129
	v_cvt_pk_bf16_f32 v50, v2, v50
	v_mul_f32_e32 v2, v132, v129
	v_mul_f32_e32 v51, v133, v129
	v_cvt_pk_bf16_f32 v51, v2, v51
	v_mul_f32_e32 v2, v134, v129
	v_mul_f32_e32 v52, v135, v129
	v_fmamk_f32 v49, v49, 0x3b800000, v204
	v_cvt_pk_bf16_f32 v52, v2, v52
	v_mul_f32_e32 v2, v136, v129
	v_mul_f32_e32 v53, v138, v129
	v_lshl_add_u64 v[122:123], v[120:121], 0, v[172:173]
	v_rsq_f32_e32 v49, v49
	v_cvt_pk_bf16_f32 v53, v2, v53
	global_store_dwordx4 v[122:123], v[50:53], off
	v_mul_f32_e32 v2, v137, v144
	v_lshl_add_u64 v[124:125], v[120:121], 0, v[174:175]
	v_mul_f32_e32 v50, v139, v144
	v_cvt_pk_bf16_f32 v50, v2, v50
	v_mul_f32_e32 v2, v140, v144
	v_mul_f32_e32 v51, v141, v144
	v_cvt_pk_bf16_f32 v51, v2, v51
	v_mul_f32_e32 v2, v142, v144
	v_mul_f32_e32 v52, v143, v144
	v_cvt_pk_bf16_f32 v52, v2, v52
	v_mul_f32_e32 v2, v83, v144
	v_mul_f32_e32 v53, v85, v144
	v_cvt_pk_bf16_f32 v53, v2, v53
	global_store_dwordx4 v[124:125], v[50:53], off
	v_mul_f32_e32 v2, v82, v49
	v_lshl_add_u64 v[82:83], v[120:121], 0, v[176:177]
	v_mul_f32_e32 v50, v84, v49
	v_cvt_pk_bf16_f32 v50, v2, v50
	v_mul_f32_e32 v2, v86, v49
	v_mul_f32_e32 v51, v87, v49
	v_cvt_pk_bf16_f32 v51, v2, v51
	v_mul_f32_e32 v2, v88, v49
	v_mul_f32_e32 v52, v89, v49
	v_cvt_pk_bf16_f32 v52, v2, v52
	v_mul_f32_e32 v2, v90, v49
	v_mul_f32_e32 v53, v93, v49
	v_cvt_pk_bf16_f32 v53, v2, v53
	global_store_dwordx4 v[82:83], v[50:53], off
	v_mul_f32_e32 v2, v91, v145
	v_lshl_add_u64 v[84:85], v[120:121], 0, v[182:183]
	v_mul_f32_e32 v50, v92, v145
	v_cvt_pk_bf16_f32 v50, v2, v50
	v_mul_f32_e32 v2, v94, v145
	v_mul_f32_e32 v51, v95, v145
	v_cvt_pk_bf16_f32 v51, v2, v51
	v_mul_f32_e32 v2, v96, v145
	v_mul_f32_e32 v52, v97, v145
	v_cvt_pk_bf16_f32 v52, v2, v52
	v_mul_f32_e32 v2, v99, v145
	v_mul_f32_e32 v53, v101, v145
	v_cvt_pk_bf16_f32 v53, v2, v53
	global_store_dwordx4 v[84:85], v[50:53], off
	v_mul_f32_e32 v2, v98, v129
	v_mul_f32_e32 v37, v37, v144
	v_mul_f32_e32 v50, v100, v129
	v_cvt_pk_bf16_f32 v50, v2, v50
	v_mul_f32_e32 v2, v102, v129
	v_mul_f32_e32 v51, v103, v129
	v_cvt_pk_bf16_f32 v51, v2, v51
	v_mul_f32_e32 v2, v104, v129
	v_mul_f32_e32 v52, v105, v129
	v_cvt_pk_bf16_f32 v52, v2, v52
	v_mul_f32_e32 v2, v106, v129
	v_mul_f32_e32 v53, v107, v129
	v_cvt_pk_bf16_f32 v53, v2, v53
	global_store_dwordx4 v[122:123], v[50:53], off offset:128
	v_mul_f32_e32 v2, v108, v144
	s_mov_b64 s[0:1], 0
	v_mul_f32_e32 v50, v109, v144
	v_cvt_pk_bf16_f32 v50, v2, v50
	v_mul_f32_e32 v2, v110, v144
	v_mul_f32_e32 v51, v111, v144
	v_cvt_pk_bf16_f32 v51, v2, v51
	v_mul_f32_e32 v2, v112, v144
	v_mul_f32_e32 v52, v113, v144
	v_cvt_pk_bf16_f32 v52, v2, v52
	v_mul_f32_e32 v2, v114, v144
	v_mul_f32_e32 v53, v55, v144
	v_cvt_pk_bf16_f32 v53, v2, v53
	global_store_dwordx4 v[124:125], v[50:53], off offset:128
	v_mul_f32_e32 v2, v54, v49
	s_nop 0
	v_mul_f32_e32 v50, v56, v49
	v_cvt_pk_bf16_f32 v50, v2, v50
	v_mul_f32_e32 v2, v57, v49
	v_mul_f32_e32 v51, v58, v49
	v_cvt_pk_bf16_f32 v51, v2, v51
	v_mul_f32_e32 v2, v59, v49
	v_mul_f32_e32 v52, v60, v49
	v_cvt_pk_bf16_f32 v52, v2, v52
	v_mul_f32_e32 v2, v61, v49
	v_mul_f32_e32 v53, v63, v49
	v_cvt_pk_bf16_f32 v53, v2, v53
	global_store_dwordx4 v[82:83], v[50:53], off offset:128
	v_mul_f32_e32 v2, v62, v145
	s_nop 0
	v_mul_f32_e32 v50, v64, v145
	v_cvt_pk_bf16_f32 v50, v2, v50
	v_mul_f32_e32 v2, v65, v145
	v_mul_f32_e32 v51, v66, v145
	v_cvt_pk_bf16_f32 v51, v2, v51
	v_mul_f32_e32 v2, v67, v145
	v_mul_f32_e32 v52, v68, v145
	v_cvt_pk_bf16_f32 v52, v2, v52
	v_mul_f32_e32 v2, v69, v145
	v_mul_f32_e32 v53, v70, v145
	v_cvt_pk_bf16_f32 v53, v2, v53
	global_store_dwordx4 v[84:85], v[50:53], off offset:128
	v_mul_f32_e32 v2, v71, v129
	s_nop 0
	v_mul_f32_e32 v50, v72, v129
	v_cvt_pk_bf16_f32 v50, v2, v50
	v_mul_f32_e32 v2, v73, v129
	v_mul_f32_e32 v51, v74, v129
	v_cvt_pk_bf16_f32 v51, v2, v51
	v_mul_f32_e32 v2, v75, v129
	v_mul_f32_e32 v52, v76, v129
	v_cvt_pk_bf16_f32 v52, v2, v52
	v_mul_f32_e32 v2, v77, v129
	v_mul_f32_e32 v53, v78, v129
	v_cvt_pk_bf16_f32 v53, v2, v53
	global_store_dwordx4 v[122:123], v[50:53], off offset:256
	v_mul_f32_e32 v2, v79, v144
	s_nop 0
	v_mul_f32_e32 v50, v80, v144
	v_cvt_pk_bf16_f32 v50, v2, v50
	v_mul_f32_e32 v2, v81, v144
	v_mul_f32_e32 v51, v115, v144
	v_cvt_pk_bf16_f32 v51, v2, v51
	v_mul_f32_e32 v2, v116, v144
	v_mul_f32_e32 v52, v117, v144
	v_cvt_pk_bf16_f32 v52, v2, v52
	v_mul_f32_e32 v2, v118, v144
	v_cvt_pk_bf16_f32 v53, v2, v37
	v_mul_f32_e32 v2, v36, v49
	v_mul_f32_e32 v36, v38, v49
	global_store_dwordx4 v[124:125], v[50:53], off offset:256
	v_cvt_pk_bf16_f32 v36, v2, v36
	v_mul_f32_e32 v2, v39, v49
	v_mul_f32_e32 v37, v40, v49
	v_cvt_pk_bf16_f32 v37, v2, v37
	v_mul_f32_e32 v2, v41, v49
	v_mul_f32_e32 v38, v42, v49
	v_cvt_pk_bf16_f32 v38, v2, v38
	v_mul_f32_e32 v2, v43, v49
	v_mul_f32_e32 v39, v45, v49
	v_cvt_pk_bf16_f32 v39, v2, v39
	global_store_dwordx4 v[82:83], v[36:39], off offset:256
	v_mul_f32_e32 v2, v44, v145
	s_nop 0
	v_mul_f32_e32 v36, v46, v145
	v_cvt_pk_bf16_f32 v36, v2, v36
	v_mul_f32_e32 v2, v47, v145
	v_mul_f32_e32 v37, v48, v145
	v_cvt_pk_bf16_f32 v37, v2, v37
	v_mul_f32_e32 v2, v119, v145
	v_mul_f32_e32 v38, v126, v145
	v_cvt_pk_bf16_f32 v38, v2, v38
	v_mul_f32_e32 v2, v127, v145
	v_mul_f32_e32 v39, v128, v145
	v_cvt_pk_bf16_f32 v39, v2, v39
	v_mul_f32_e32 v2, v4, v129
	v_mul_f32_e32 v4, v6, v129
	global_store_dwordx4 v[84:85], v[36:39], off offset:256
	v_cvt_pk_bf16_f32 v4, v2, v4
	v_mul_f32_e32 v2, v5, v129
	v_mul_f32_e32 v5, v7, v129
	v_cvt_pk_bf16_f32 v5, v2, v5
	v_mul_f32_e32 v2, v8, v129
	v_mul_f32_e32 v6, v10, v129
	v_cvt_pk_bf16_f32 v6, v2, v6
	v_mul_f32_e32 v2, v9, v129
	v_mul_f32_e32 v7, v11, v129
	v_cvt_pk_bf16_f32 v7, v2, v7
	global_store_dwordx4 v[122:123], v[4:7], off offset:384
	v_mul_f32_e32 v2, v12, v144
	s_nop 0
	v_mul_f32_e32 v4, v14, v144
	v_cvt_pk_bf16_f32 v4, v2, v4
	v_mul_f32_e32 v2, v13, v144
	v_mul_f32_e32 v5, v15, v144
	v_cvt_pk_bf16_f32 v5, v2, v5
	v_mul_f32_e32 v2, v16, v144
	v_mul_f32_e32 v6, v18, v144
	v_cvt_pk_bf16_f32 v6, v2, v6
	v_mul_f32_e32 v2, v17, v144
	v_mul_f32_e32 v7, v19, v144
	v_cvt_pk_bf16_f32 v7, v2, v7
	global_store_dwordx4 v[124:125], v[4:7], off offset:384
	v_mul_f32_e32 v2, v20, v49
	s_nop 0
	v_mul_f32_e32 v4, v22, v49
	v_cvt_pk_bf16_f32 v4, v2, v4
	v_mul_f32_e32 v2, v21, v49
	v_mul_f32_e32 v5, v23, v49
	v_cvt_pk_bf16_f32 v5, v2, v5
	v_mul_f32_e32 v2, v24, v49
	v_mul_f32_e32 v6, v26, v49
	v_cvt_pk_bf16_f32 v6, v2, v6
	v_mul_f32_e32 v2, v25, v49
	v_mul_f32_e32 v7, v27, v49
	v_cvt_pk_bf16_f32 v7, v2, v7
	global_store_dwordx4 v[82:83], v[4:7], off offset:384
	v_mul_f32_e32 v2, v28, v145
	s_nop 0
	v_mul_f32_e32 v4, v30, v145
	v_cvt_pk_bf16_f32 v4, v2, v4
	v_mul_f32_e32 v2, v29, v145
	v_mul_f32_e32 v5, v31, v145
	v_cvt_pk_bf16_f32 v5, v2, v5
	v_mul_f32_e32 v2, v32, v145
	v_mul_f32_e32 v6, v34, v145
	v_mul_f32_e32 v7, v35, v145
	v_cvt_pk_bf16_f32 v6, v2, v6
	v_mul_f32_e32 v2, v33, v145
	v_cvt_pk_bf16_f32 v7, v2, v7
	global_store_dwordx4 v[84:85], v[4:7], off offset:384
	s_waitcnt lgkmcnt(0)
	s_barrier
